# diff attention PV on v_mfma_f32_16x16x32_bf16 (P fragments via v_permlane16_swap, O layout restored through LDS at unit exit); QK stays 32x32x16
# baseline (speedup 1.0000x reference)
; #define ALAS __attribute__((address_space(3)))
; #define AT_DMA(tr) do { const unsigned sb_ = (unsigned)__builtin_amdgcn_readfirstlane(dk + (((tr) & (NSTG - 1)) * STAGE)); const size_t ko_ = (size_t)(tr) * 26 * 4096, vo_ = (size_t)(tr) * 640 * 64; \
;         glds16(kg + ko_, sb_ + OFF_K0); if (!WIN) glds16(kg + ko_ + 4096, sb_ + OFF_K1); glds16(vg + vo_, sb_ + OFF_V); if (!WIN) glds16(vg + vo_ + 64 * 64, sb_ + OFF_V + 8192); } while (0)
; template <bool WIN> ...
;     ...
;     const int tid = threadIdx.x, lane = tid & 63, l31 = lane & 31, hi = lane >> 5;
;     const int wid = __builtin_amdgcn_readfirstlane(tid >> 6), half = wid >> 2, wq = wid & 3;
;     const int qw = q0 + 32 * wq;
;     int qcol, kcol0, kcol1, vrow0, bhead;
;     if (WIN) { qcol = (2 * hsel + half) * 64; kcol0 = 512 + (hsel >> 1) * 64; kcol1 = kcol0; vrow0 = (hsel >> 1) * 64; bhead = 2 * hsel; }
;     else { qcol = 640 + (2 * hsel + half) * 64; kcol0 = 1152 + (2 * hsel) * 64; kcol1 = kcol0 + 64; vrow0 = 128 + hsel * 128; bhead = 8 + hsel; }
;     const ALAS float* lut = (const ALAS float*)(lds + OFF_LUT) + (WIN ? (bhead + half) : bhead) * LUTW;
;     const int t_lo = WIN ? (q0 >= 128 ? (q0 - 128) / 64 : 0) : 0;
;     const int t_hi = WIN ? ((q0 + 256) / 64 < S / 64 ? (q0 + 256) / 64 : S / 64) : S / 64;
;     const int NT = t_hi - t_lo;
;     const unsigned ldsb = (unsigned)(uintptr_t)lds;
;     const int drow = 8 * wid + (lane >> 3), dch = (lane & 7) ^ ((4 * wid + (lane >> 4)) & 7);
;     const bf16_t* kg = QK + ((size_t)((seq_base >> 6) + t_lo) * 26 * 64 + drow) * 64 + dch * 8 + kcol0 * 64;
;     const bf16_t* vg = VT + ((size_t)((seq_base >> 6) + t_lo) * 640 + vrow0 + drow) * 64 + dch * 8;
;     const unsigned dk = ldsb + wid * 1024;
;     ...
;     constexpr int NPW = WIN ? 2 : 4;
;     bf16x8 qfr[4];
;     { const int qrow = seq_base + qw + l31; const bf16_t* qp = QK + ((size_t)((qrow >> 6) * 26 + (qcol >> 6)) * 64 + (qrow & 63)) * 64 + hi * 8;
; #pragma unroll
;       for (int ds = 0; ds < 4; ++ds) qfr[ds] = *(const bf16x8*)(qp + ds * 16); }
;     ...
;     AT_DMA(0); if (NT > 1) AT_DMA(1); if (NT > 2) AT_DMA(2);
.LBB0_244:
	s_lshl_b32 s62, s33, 5
	s_lshl_b32 s20, s33, 2
	s_and_b32 s62, s62, 32
	v_readfirstlane_b32 s64, v230
	s_and_b32 s20, s20, 24
	s_add_i32 s62, s62, s22
	s_bfe_u32 s77, s64, 0x20006
	s_or_b32 s20, s20, s24
	s_lshl_b32 s62, s62, 7
	s_lshl_b32 s82, s77, 5
	s_lshl_b32 s20, s20, 11
	s_or_b32 s78, s82, s62
	s_and_b32 s20, s20, 0xe000
	s_lshr_b32 s76, s64, 8
	v_or_b32_e32 v4, s78, v185
	v_add_u32_e32 v170, s20, v4
	s_add_i32 s62, s76, s66
	v_ashrrev_i32_e32 v2, 6, v170
	v_mov_b32_e32 v0, s62
	v_mad_u64_u32 v[2:3], s[62:63], v2, 26, v[0:1]
	v_ashrrev_i32_e32 v3, 31, v2
	v_lshlrev_b64 v[2:3], 13, v[2:3]
	v_lshlrev_b32_e32 v0, 7, v4
	v_lshl_add_u64 v[2:3], s[6:7], 0, v[2:3]
	v_and_b32_e32 v4, 0x1f80, v0
	v_mov_b32_e32 v5, v1
	v_lshl_add_u64 v[2:3], v[2:3], 0, v[4:5]
	v_lshl_add_u64 v[2:3], v[2:3], 0, v[164:165]
	global_load_dwordx4 v[114:117], v[2:3], off offset:96
	global_load_dwordx4 v[118:121], v[2:3], off offset:64
	global_load_dwordx4 v[122:125], v[2:3], off offset:32
	global_load_dwordx4 v[126:129], v[2:3], off
	s_lshl_b32 s62, s31, 11
	s_and_b32 s62, s62, 0xffffc000
	s_or_b32 s62, s26, s62
	v_cndmask_b32_e64 v0, 0, 1, s[38:39]
	s_lshr_b32 s81, s62, 13
	v_readfirstlane_b32 s62, v0
	s_lshr_b32 s63, s64, 4
	s_lshl_b32 s83, s62, 12
	s_lshr_b32 s62, s64, 6
	s_and_b32 s63, s63, 4
	s_lshl_b32 s84, s62, 3
	v_bitop3_b32 v4, s63, v186, v189 bitop3:0x36
	s_lshr_b32 s63, s20, 6
	v_or_b32_e32 v0, s84, v188
	s_mul_i32 s20, s63, 0x680
	v_lshl_add_u64 v[2:3], s[20:21], 0, v[0:1]
	v_lshlrev_b64 v[2:3], 7, v[2:3]
	v_lshl_add_u64 v[2:3], s[6:7], 0, v[2:3]
	v_lshlrev_b32_e32 v4, 4, v4
	v_lshl_add_u64 v[2:3], v[2:3], 0, v[4:5]
	s_mul_i32 s20, s63, 0x280
	v_add_u32_e32 v6, s12, v0
	v_mov_b32_e32 v7, v1
	v_lshl_add_u64 v[2:3], v[2:3], 0, s[18:19]
	v_lshl_add_u64 v[6:7], v[6:7], 0, s[20:21]
	s_lshl_b32 s20, s62, 10
	s_mov_b64 s[62:63], 0x24000
	v_lshl_add_u64 v[8:9], v[2:3], 0, s[62:63]
	s_add_i32 s20, s20, 0
	s_mov_b32 s62, m0
	s_mov_b32 m0, s20
	s_nop 0
	global_load_lds_dwordx4 v[8:9], off
	s_mov_b32 m0, s62
	s_mov_b64 s[62:63], 0x26000
	v_lshlrev_b64 v[6:7], 7, v[6:7]
	v_lshl_add_u64 v[8:9], v[2:3], 0, s[62:63]
	s_add_i32 s62, s20, 0x2000
	v_lshl_add_u64 v[6:7], s[4:5], 0, v[6:7]
	s_mov_b32 s63, m0
	s_mov_b32 m0, s62
	s_nop 0
	global_load_lds_dwordx4 v[8:9], off
	s_mov_b32 m0, s63
	s_add_i32 s62, s20, 0x4000
	v_lshl_add_u64 v[6:7], v[6:7], 0, v[4:5]
	s_mov_b32 s63, m0
	s_mov_b32 m0, s62
	s_nop 0
	global_load_lds_dwordx4 v[6:7], off
	s_mov_b32 m0, s63
	s_add_i32 s62, s20, 0x6000
	v_lshl_add_u64 v[8:9], v[6:7], 0, s[40:41]
	s_mov_b32 s63, m0
	s_mov_b32 m0, s62
	s_nop 0
	global_load_lds_dwordx4 v[8:9], off
	s_mov_b32 m0, s63
	s_add_i32 s62, s20, 0x8000
	v_lshl_add_u64 v[8:9], v[2:3], 0, s[42:43]
	s_mov_b32 s63, m0
	s_mov_b32 m0, s62
	s_nop 0
	global_load_lds_dwordx4 v[8:9], off
	s_mov_b32 m0, s63
	s_add_i32 s62, s20, 0xa000
	v_lshl_add_u64 v[8:9], v[2:3], 0, s[46:47]
	s_mov_b32 s63, m0
	s_mov_b32 m0, s62
	s_nop 0
	global_load_lds_dwordx4 v[8:9], off
	s_mov_b32 m0, s63
	s_add_i32 s62, s20, 0xc000
	v_lshl_add_u64 v[8:9], v[6:7], 0, s[48:49]
	s_mov_b32 s63, m0
	s_mov_b32 m0, s62
	s_nop 0
	global_load_lds_dwordx4 v[8:9], off
	s_mov_b32 m0, s63
	s_add_i32 s62, s20, 0xe000
	v_lshl_add_u64 v[8:9], v[6:7], 0, s[50:51]
	s_mov_b32 s63, m0
	s_mov_b32 m0, s62
	s_nop 0
	global_load_lds_dwordx4 v[8:9], off
	s_mov_b32 m0, s63
	s_add_i32 s62, s20, 0x10000
	v_lshl_add_u64 v[8:9], v[2:3], 0, s[52:53]
	s_mov_b32 s63, m0
	s_mov_b32 m0, s62
	s_nop 0
	global_load_lds_dwordx4 v[8:9], off
	s_mov_b32 m0, s63
	s_add_i32 s62, s20, 0x12000
	v_lshl_add_u64 v[2:3], v[2:3], 0, s[54:55]
	s_mov_b32 s63, m0
	s_mov_b32 m0, s62
	s_nop 0
	global_load_lds_dwordx4 v[2:3], off
	s_mov_b32 m0, s63
	s_add_i32 s62, s20, 0x14000
	v_lshl_add_u64 v[2:3], v[6:7], 0, s[56:57]
	s_add_i32 s62, s20, 0x16000
	v_lshl_add_u64 v[2:3], v[6:7], 0, s[58:59]
	s_cmpk_lt_u32 s64, 0x100
	s_cselect_b64 s[62:63], -1, 0
	s_and_b64 s[64:65], s[62:63], exec
	s_cselect_b32 s64, 0, 0x2000
	s_add_i32 s67, s27, 0x20000
	v_mov_b32_e32 v2, s67
	ds_read_b32 v3, v2 offset:14336
	ds_read_b32 v2, v2 offset:16124
	v_or_b32_e32 v162, s64, v177
	v_mov_b32_e32 v14, v1
	v_mov_b32_e32 v15, v1
	s_waitcnt lgkmcnt(1)
; __device__ __forceinline__ int pi32(int r) { return (r & ~12) | ((r & 4) << 1) | ((r & 8) >> 1); }
; template <bool WIN> ...
;     ...
;     float m_ref = WIN ? sinkp[2 * hsel + half] * LOG2E : 0.f;
;     float l_run = (WIN && hi == 0) ? 1.f : 0.f;
;     float cbase = 0.f;
;     f32x16 cvec;
; #pragma unroll
;     for (int r = 0; r < 16; ++r) cvec[r] = cbase - m_ref;
;     f32x16 o[NDB];
; #pragma unroll
;     for (int db = 0; db < NDB; ++db)
; #pragma unroll
;         for (int r = 0; r < 16; ++r) o[db][r] = 0.f;
;     const int krow = pi32(l31), fK = (krow >> 1) & 7, fV = (l31 >> 1) & 7;
;     int kx[4], vx[4];
; #pragma unroll
;     for (int c = 0; c < 4; ++c) { kx[c] = (WIN ? OFF_K0 : (half ? OFF_K1 : OFF_K0)) + krow * 128 + (((2 * c + hi) ^ fK) << 4); vx[c] = OFF_V + l31 * 128 + (((2 * c + hi) ^ fV) << 4); }
;     const int qabs = qw + l31;
;     const float cfar_lo = __uint_as_float(__builtin_amdgcn_readfirstlane(__float_as_uint(lut[0]))), cfar_hi = __uint_as_float(__builtin_amdgcn_readfirstlane(__float_as_uint(lut[LUTW - 1])));
;     asm volatile("" : "+v"(qfr[0]), "+v"(qfr[1]), "+v"(qfr[2]), "+v"(qfr[3]));
	v_readfirstlane_b32 s79, v3
	s_waitcnt lgkmcnt(0)
	v_readfirstlane_b32 s80, v2
	v_add_u32_e32 v2, s84, v197
	v_mov_b32_e32 v3, v1
	v_lshlrev_b64 v[2:3], 7, v[2:3]
	v_mad_u64_u32 v[2:3], s[64:65], s81, v199, v[2:3]
	v_or_b32_e32 v2, v2, v4
	v_lshl_add_u64 v[172:173], s[36:37], 0, v[2:3]
	v_lshlrev_b64 v[2:3], 7, v[0:1]
	v_mad_u64_u32 v[2:3], s[64:65], s81, v200, v[2:3]
	s_or_b32 s64, s82, s83
	v_or_b32_e32 v2, v2, v4
	v_add_lshl_u32 v0, s64, v198, 2
	v_lshl_add_u64 v[174:175], s[16:17], 0, v[2:3]
	v_sub_u32_e32 v171, v195, v0
	s_sub_i32 s64, s28, s82
	v_mov_b32_e32 v0, v1
	v_mov_b32_e32 v2, v1
	v_mov_b32_e32 v3, v1
	v_mov_b32_e32 v4, v1
	v_mov_b32_e32 v6, v1
	v_mov_b32_e32 v7, v1
	v_mov_b32_e32 v8, v1
	v_mov_b32_e32 v9, v1
	v_mov_b32_e32 v10, v1
	v_mov_b32_e32 v11, v1
	v_mov_b32_e32 v12, v1
	v_mov_b32_e32 v13, v1
	v_mov_b64_e32 v[64:65], v[14:15]
	v_mov_b64_e32 v[48:49], v[14:15]
	v_mov_b64_e32 v[32:33], v[14:15]
	s_sub_i32 s81, s64, s83
	s_add_i32 s64, s29, s83
	v_mov_b64_e32 v[62:63], v[12:13]
	v_mov_b64_e32 v[60:61], v[10:11]
	v_mov_b64_e32 v[58:59], v[8:9]
	v_mov_b64_e32 v[56:57], v[6:7]
	v_mov_b64_e32 v[54:55], v[4:5]
	v_mov_b64_e32 v[52:53], v[2:3]
	v_mov_b64_e32 v[50:51], v[0:1]
	v_mov_b64_e32 v[46:47], v[12:13]
	v_mov_b64_e32 v[44:45], v[10:11]
	v_mov_b64_e32 v[42:43], v[8:9]
	v_mov_b64_e32 v[40:41], v[6:7]
	v_mov_b64_e32 v[38:39], v[4:5]
	v_mov_b64_e32 v[36:37], v[2:3]
	v_mov_b64_e32 v[34:35], v[0:1]
	v_mov_b64_e32 v[30:31], v[12:13]
	v_mov_b64_e32 v[28:29], v[10:11]
	v_mov_b64_e32 v[26:27], v[8:9]
	v_mov_b64_e32 v[24:25], v[6:7]
	v_mov_b64_e32 v[22:23], v[4:5]
	v_mov_b64_e32 v[20:21], v[2:3]
	v_mov_b64_e32 v[18:19], v[0:1]
	v_mov_b64_e32 v[16:17], v[14:15]
	s_add_i32 s82, s64, s82
	s_mov_b32 s83, 0
	s_mov_b32 s84, 0
	s_mov_b32 s85, 0x10000
	v_mov_b64_e32 v[14:15], v[12:13]
	v_mov_b64_e32 v[12:13], v[10:11]
	v_mov_b64_e32 v[10:11], v[8:9]
	v_mov_b64_e32 v[8:9], v[6:7]
	v_mov_b64_e32 v[6:7], v[4:5]
	v_mov_b64_e32 v[4:5], v[2:3]
	v_mov_b64_e32 v[2:3], v[0:1]
	v_mov_b32_e32 v0, 0
	v_mov_b32_e32 v196, 0
	v_mov_b32_e32 v202, 0
	s_mov_b32 s86, 0
	v_mov_b32_e32 v66, 0
	v_mov_b32_e32 v67, v1
	v_mov_b32_e32 v68, v1
	v_mov_b32_e32 v69, v1
	v_mov_b32_e32 v70, v1
	v_mov_b32_e32 v71, v1
	v_mov_b32_e32 v72, v1
	v_mov_b32_e32 v73, v1
	v_mov_b32_e32 v74, v1
	v_mov_b32_e32 v75, v1
	v_mov_b32_e32 v76, v1
	v_mov_b32_e32 v77, v1
	v_mov_b32_e32 v78, v1
	v_mov_b32_e32 v79, v1
	v_mov_b32_e32 v80, v1
	v_mov_b32_e32 v81, v1
	s_mov_b32 s98, 0xfffec000
	s_mov_b32 s99, -1
	v_lshl_add_u64 v[172:173], v[172:173], 0, s[98:99]
	s_mov_b32 s98, 0xfffcc000
	s_waitcnt vmcnt(10)
	v_mbcnt_lo_u32_b32 v82, -1, 0
	v_mbcnt_hi_u32_b32 v82, -1, v82
	v_and_b32_e32 v83, 15, v82
	v_lshrrev_b32_e32 v84, 2, v83
	v_and_b32_e32 v85, 3, v83
	v_lshrrev_b32_e32 v86, 1, v84
	v_xor_b32_e32 v87, v86, v84
	v_and_b32_e32 v87, 1, v87
	v_xor_b32_e32 v87, 1, v87
	v_lshlrev_b32_e32 v87, 1, v87
	v_lshl_add_u32 v87, v86, 3, v87
	v_and_b32_e32 v88, 1, v85
	v_add_u32_e32 v87, v87, v88
	v_lshrrev_b32_e32 v88, 1, v85
	v_lshl_add_u32 v87, v88, 2, v87
	v_lshrrev_b32_e32 v88, 1, v87
	v_lshrrev_b32_e32 v89, 4, v82
	v_lshrrev_b32_e32 v90, 1, v89
	v_and_b32_e32 v89, 1, v89
	v_lshl_or_b32 v89, v89, 1, v90
	v_xor_b32_e32 v88, v88, v89
	v_lshlrev_b32_e32 v88, 4, v88
	v_lshl_add_u32 v179, v87, 7, v88
	v_xor_b32_e32 v181, 64, v179
	s_branch .LSPp_top

; #define ALAS __attribute__((address_space(3)))
; #define MX3(a, b, c) __builtin_fmaxf(__builtin_fmaxf((a), (b)), (c))
; template <bool WIN> ...
;     ...
;             const ALAS unsigned char* sb = lds + (tr & (NSTG - 1)) * STAGE;
;             {
;                 bf16x8 ka[8];
; #pragma unroll
;                 for (int ds = 0; ds < 4; ++ds) { ka[2 * ds] = *(const ALAS bf16x8*)(sb + kx[ds]); ka[2 * ds + 1] = *(const ALAS bf16x8*)(sb + kx[ds] + 4096); }
;                 __builtin_amdgcn_sched_barrier(0);
;                 s0 = __builtin_amdgcn_mfma_f32_32x32x16_bf16(ka[0], qf(0), cvec, 0, 0, 0);
;                 s1 = __builtin_amdgcn_mfma_f32_32x32x16_bf16(ka[1], qf(0), cvec, 0, 0, 0);
; #pragma unroll
;                 for (int ds = 1; ds < 4; ++ds) {
;                     s0 = __builtin_amdgcn_mfma_f32_32x32x16_bf16(ka[2 * ds], qf(ds), s0, 0, 0, 0);
;                     s1 = __builtin_amdgcn_mfma_f32_32x32x16_bf16(ka[2 * ds + 1], qf(ds), s1, 0, 0, 0);
;                 }
;             }
;             bf16x8 va[2 * NDB], vc[2 * NDB];
; #pragma unroll
;             for (int kk = 0; kk < 2; ++kk)
; #pragma unroll
;                 for (int db = 0; db < NDB; ++db) va[kk * NDB + db] = *(const ALAS bf16x8*)(sb + vx[kk] + db * 4096);
;             __builtin_amdgcn_sched_barrier(0);
;             if (near) {
;                 const ALAS float* lb = lut + (k0 + 8 * hi - qabs + LUTC);
; #pragma unroll
;                 for (int r = 0; r < 16; ++r) { s0[r] += lb[16 * (r >> 3) + (r & 7)]; s1[r] += lb[32 + 16 * (r >> 3) + (r & 7)];
;                     if ((r & 7) == 7) __builtin_amdgcn_sched_barrier(0); }
;             }
;     ...
;             float mxa = MX3(s0[0], s0[1], s1[0]), mxb = MX3(s0[2], s0[3], s1[1]);
;             mxa = MX3(mxa, s1[2], s1[3]);
; #pragma unroll
;             for (int r = 4; r < 16; r += 4) { mxa = MX3(mxa, s0[r], s0[r + 1]); mxb = MX3(mxb, s0[r + 2], s0[r + 3]); mxa = MX3(mxa, s1[r], s1[r + 1]); mxb = MX3(mxb, s1[r + 2], s1[r + 3]); }
;     ...
;             float mx = fmaxf(mxa, mxb);
;             if (__any(mx > THR)) {
.LSPp_qk:
	s_add_i32 s87, s85, 0xffff0000
	s_and_b32 s87, s87, 0x18000
	s_add_i32 s99, s85, 0xfffe8000
	s_and_b32 s99, s99, 0x18000
	v_add3_u32 v203, s87, v178, v162
	ds_read_b128 v[130:133], v203
	ds_read_b128 v[134:137], v203 offset:4096
	v_add3_u32 v203, s87, v180, v162
	ds_read_b128 v[138:141], v203
	ds_read_b128 v[142:145], v203 offset:4096
	v_add3_u32 v203, s87, v182, v162
	ds_read_b128 v[146:149], v203
	ds_read_b128 v[150:153], v203 offset:4096
	v_add3_u32 v203, s87, v184, v162
	ds_read_b128 v[158:161], v203
	ds_read_b128 v[204:207], v203 offset:4096
	s_waitcnt lgkmcnt(0)
	v_mfma_f32_32x32x16_bf16 v[98:113], v[130:133], v[126:129], v[66:81]
	v_mfma_f32_32x32x16_bf16 v[82:97], v[134:137], v[126:129], v[66:81]
	v_mfma_f32_32x32x16_bf16 v[98:113], v[138:141], v[122:125], v[98:113]
	v_mfma_f32_32x32x16_bf16 v[82:97], v[142:145], v[122:125], v[82:97]
	v_mfma_f32_32x32x16_bf16 v[98:113], v[146:149], v[118:121], v[98:113]
	v_mfma_f32_32x32x16_bf16 v[82:97], v[150:153], v[118:121], v[82:97]
	v_mfma_f32_32x32x16_bf16 v[98:113], v[158:161], v[114:117], v[98:113]
	v_mfma_f32_32x32x16_bf16 v[82:97], v[204:207], v[114:117], v[82:97]
	v_add_u32_e32 v236, s99, v179
	ds_read_b128 v[146:149], v236 offset:16384
	ds_read_b128 v[150:153], v236 offset:18432
	ds_read_b128 v[154:157], v236 offset:20480
	ds_read_b128 v[158:161], v236 offset:22528
	v_add_u32_e32 v237, s99, v179
	ds_read_b128 v[130:133], v237 offset:24576
	ds_read_b128 v[134:137], v237 offset:26624
	ds_read_b128 v[138:141], v237 offset:28672
	ds_read_b128 v[142:145], v237 offset:30720
	s_nop 1
	s_andn2_b64 vcc, exec, s[64:65]
	s_cbranch_vccnz .LSPp_max
	v_add_u32_e32 v203, s84, v171
	v_add_u32_e32 v204, 0x23b80, v203
	v_add_u32_e32 v206, 0x23c00, v203
	v_add_u32_e32 v210, 0x23c08, v203
	v_add_u32_e32 v208, 0x23b88, v203
	v_add_u32_e32 v218, 0x23c10, v203
	v_add_u32_e32 v212, 0x23b90, v203
	v_add_u32_e32 v216, 0x23c18, v203
	v_add_u32_e32 v214, 0x23b98, v203
	ds_read2_b32 v[204:205], v204 offset1:1
	ds_read2_b32 v[206:207], v206 offset1:1
	ds_read2_b32 v[208:209], v208 offset1:1
	ds_read2_b32 v[210:211], v210 offset1:1
	ds_read2_b32 v[212:213], v212 offset1:1
	ds_read2_b32 v[214:215], v214 offset1:1
	ds_read2_b32 v[216:217], v216 offset1:1
	ds_read2_b32 v[218:219], v218 offset1:1
	v_add_u32_e32 v220, 0x23bc0, v203
	v_add_u32_e32 v222, 0x23c40, v203
	v_add_u32_e32 v226, 0x23c48, v203
	v_add_u32_e32 v224, 0x23bc8, v203
	v_add_u32_e32 v228, 0x23bd0, v203
	v_add_u32_e32 v234, 0x23c58, v203
	ds_read2_b32 v[220:221], v220 offset1:1
	ds_read2_b32 v[222:223], v222 offset1:1
	ds_read2_b32 v[224:225], v224 offset1:1
	ds_read2_b32 v[226:227], v226 offset1:1
	v_add_u32_e32 v231, 0x23c50, v203
	v_add_u32_e32 v203, 0x23bd8, v203
	ds_read2_b32 v[228:229], v228 offset1:1
	ds_read2_b32 v[232:233], v203 offset1:1
	ds_read2_b32 v[234:235], v234 offset1:1
	ds_read2_b32 v[236:237], v231 offset1:1
	s_waitcnt lgkmcnt(10)
	v_pk_add_f32 v[104:105], v[104:105], v[214:215]
	v_pk_add_f32 v[102:103], v[102:103], v[212:213]
	v_pk_add_f32 v[100:101], v[100:101], v[208:209]
	s_waitcnt lgkmcnt(2)
	v_pk_add_f32 v[112:113], v[112:113], v[232:233]
	v_pk_add_f32 v[110:111], v[110:111], v[228:229]
	v_pk_add_f32 v[108:109], v[108:109], v[224:225]
	v_pk_add_f32 v[106:107], v[106:107], v[220:221]
	v_pk_add_f32 v[98:99], v[98:99], v[204:205]
	v_pk_add_f32 v[88:89], v[88:89], v[216:217]
	v_pk_add_f32 v[86:87], v[86:87], v[218:219]
	v_pk_add_f32 v[84:85], v[84:85], v[210:211]
	s_waitcnt lgkmcnt(1)
	v_pk_add_f32 v[96:97], v[96:97], v[234:235]
	s_waitcnt lgkmcnt(0)
	v_pk_add_f32 v[94:95], v[94:95], v[236:237]
	v_pk_add_f32 v[92:93], v[92:93], v[226:227]
	v_pk_add_f32 v[90:91], v[90:91], v[222:223]
	v_pk_add_f32 v[82:83], v[82:83], v[206:207]
.LSPp_max:
	s_nop 0
	v_max_f32_e32 v203, v99, v99
	v_max_f32_e32 v204, v98, v98
	v_max_f32_e32 v203, v204, v203
	s_nop 5
	v_max3_f32 v204, v100, v101, v83
	v_max3_f32 v203, v203, v82, v84
	v_max3_f32 v203, v203, v85, v102
	v_max3_f32 v204, v204, v104, v105
	v_max3_f32 v203, v203, v103, v86
	v_max3_f32 v204, v204, v88, v89
	v_max3_f32 v203, v203, v87, v106
	v_max3_f32 v204, v204, v108, v109
	v_max3_f32 v203, v203, v107, v90
	v_max3_f32 v204, v204, v92, v93
	v_max3_f32 v203, v203, v91, v110
	v_max3_f32 v204, v204, v112, v113
	v_max3_f32 v203, v203, v111, v94
	v_max3_f32 v204, v204, v96, v97
	v_max3_f32 v203, v203, v95, v204
	v_cmp_lt_f32_e32 vcc, s30, v203
	s_cbranch_vccz .LSPp_pv
	s_cmp_eq_u32 s86, 0
	s_cbranch_scc1 .LSPp_rnopv
; template <bool WIN> ...
;     ...
;                 mx = fmaxf(mx, __shfl_xor(mx, 32));
;                 const float dl = fmaxf(mx, 0.f);
;                 m_ref += dl;
;                 const float f = __builtin_amdgcn_exp2f(-dl);
;                 l_run *= f;
; #pragma unroll
;                 for (int db = 0; db < NDB; ++db)
; #pragma unroll
;                     for (int r = 0; r < 16; ++r) o[db][r] *= f;
; #pragma unroll
;                 for (int r = 0; r < 16; ++r) { s0[r] -= dl; s1[r] -= dl; cvec[r] = cbase - m_ref; }
;     ...
;             for (int db = 0; db < NDB; ++db) o[db] = __builtin_amdgcn_mfma_f32_32x32x16_bf16(va[db], p0.b, o[db], 0, 0, 0);
;             AT_EXP(s0, 8, p1);
;             __builtin_amdgcn_sched_barrier(0);
; #pragma unroll
;             for (int db = 0; db < NDB; ++db) o[db] = __builtin_amdgcn_mfma_f32_32x32x16_bf16(va[NDB + db], p1.b, o[db], 0, 0, 0);
;             AT_EXP(s1, 0, p2);
;             __builtin_amdgcn_sched_barrier(0);
; #pragma unroll
;             for (int db = 0; db < NDB; ++db) o[db] = __builtin_amdgcn_mfma_f32_32x32x16_bf16(vc[db], p2.b, o[db], 0, 0, 0);
;             AT_EXP(s1, 8, p3);
;             __builtin_amdgcn_sched_barrier(0);
; #pragma unroll
;             for (int db = 0; db < NDB; ++db) o[db] = __builtin_amdgcn_mfma_f32_32x32x16_bf16(vc[NDB + db], p3.b, o[db], 0, 0, 0);
	s_waitcnt lgkmcnt(0)
	v_add_u32_e32 v236, s99, v179
	ds_read_b128 v[146:149], v236 offset:16384
	ds_read_b128 v[150:153], v236 offset:18432
	ds_read_b128 v[154:157], v236 offset:20480
	ds_read_b128 v[158:161], v236 offset:22528
	v_add_u32_e32 v237, s99, v179
	ds_read_b128 v[130:133], v237 offset:24576
	ds_read_b128 v[134:137], v237 offset:26624
	ds_read_b128 v[138:141], v237 offset:28672
	ds_read_b128 v[142:145], v237 offset:30720
	s_waitcnt lgkmcnt(4)
	v_mfma_f32_16x16x32_bf16 v[2:5], v[146:149], v[238:241], v[2:5]
	v_mfma_f32_16x16x32_bf16 v[6:9], v[146:149], v[242:245], v[6:9]
	v_mfma_f32_16x16x32_bf16 v[10:13], v[150:153], v[238:241], v[10:13]
	v_mfma_f32_16x16x32_bf16 v[14:17], v[150:153], v[242:245], v[14:17]
	v_mfma_f32_16x16x32_bf16 v[18:21], v[154:157], v[238:241], v[18:21]
	v_mfma_f32_16x16x32_bf16 v[22:25], v[154:157], v[242:245], v[22:25]
	v_mfma_f32_16x16x32_bf16 v[26:29], v[158:161], v[238:241], v[26:29]
	v_mfma_f32_16x16x32_bf16 v[30:33], v[158:161], v[242:245], v[30:33]
	v_add_u32_e32 v236, s99, v181
	ds_read_b128 v[146:149], v236 offset:16384
	ds_read_b128 v[150:153], v236 offset:18432
	ds_read_b128 v[154:157], v236 offset:20480
	ds_read_b128 v[158:161], v236 offset:22528
	s_waitcnt lgkmcnt(4)
	v_mfma_f32_16x16x32_bf16 v[34:37], v[130:133], v[238:241], v[34:37]
	v_mfma_f32_16x16x32_bf16 v[38:41], v[130:133], v[242:245], v[38:41]
	v_mfma_f32_16x16x32_bf16 v[42:45], v[134:137], v[238:241], v[42:45]
	v_mfma_f32_16x16x32_bf16 v[46:49], v[134:137], v[242:245], v[46:49]
	v_mfma_f32_16x16x32_bf16 v[50:53], v[138:141], v[238:241], v[50:53]
	v_mfma_f32_16x16x32_bf16 v[54:57], v[138:141], v[242:245], v[54:57]
	v_mfma_f32_16x16x32_bf16 v[58:61], v[142:145], v[238:241], v[58:61]
	v_mfma_f32_16x16x32_bf16 v[62:65], v[142:145], v[242:245], v[62:65]
	v_add_u32_e32 v237, s99, v181
	ds_read_b128 v[130:133], v237 offset:24576
	ds_read_b128 v[134:137], v237 offset:26624
	ds_read_b128 v[138:141], v237 offset:28672
	ds_read_b128 v[142:145], v237 offset:30720
	s_waitcnt lgkmcnt(4)
	v_mfma_f32_16x16x32_bf16 v[2:5], v[146:149], v[246:249], v[2:5]
	v_mfma_f32_16x16x32_bf16 v[6:9], v[146:149], v[250:253], v[6:9]
	v_mfma_f32_16x16x32_bf16 v[10:13], v[150:153], v[246:249], v[10:13]
	v_mfma_f32_16x16x32_bf16 v[14:17], v[150:153], v[250:253], v[14:17]
	v_mfma_f32_16x16x32_bf16 v[18:21], v[154:157], v[246:249], v[18:21]
	v_mfma_f32_16x16x32_bf16 v[22:25], v[154:157], v[250:253], v[22:25]
	v_mfma_f32_16x16x32_bf16 v[26:29], v[158:161], v[246:249], v[26:29]
	v_mfma_f32_16x16x32_bf16 v[30:33], v[158:161], v[250:253], v[30:33]
	s_waitcnt lgkmcnt(0)
	v_mfma_f32_16x16x32_bf16 v[34:37], v[130:133], v[246:249], v[34:37]
	v_mfma_f32_16x16x32_bf16 v[38:41], v[130:133], v[250:253], v[38:41]
	v_mfma_f32_16x16x32_bf16 v[42:45], v[134:137], v[246:249], v[42:45]
	v_mfma_f32_16x16x32_bf16 v[46:49], v[134:137], v[250:253], v[46:49]
	v_mfma_f32_16x16x32_bf16 v[50:53], v[138:141], v[246:249], v[50:53]
	v_mfma_f32_16x16x32_bf16 v[54:57], v[138:141], v[250:253], v[54:57]
	v_mfma_f32_16x16x32_bf16 v[58:61], v[142:145], v[246:249], v[58:61]
	v_mfma_f32_16x16x32_bf16 v[62:65], v[142:145], v[250:253], v[62:65]
	s_nop 7
	s_nop 7
.LSPp_rnopv:
	ds_bpermute_b32 v66, v176, v203
	s_waitcnt lgkmcnt(0)
	v_max3_f32 v68, v203, v66, 0
	v_exp_f32_e64 v70, -v68
	v_add_f32_e32 v196, v196, v68
	v_sub_f32_e32 v66, v202, v196
	v_pk_add_f32 v[98:99], v[98:99], v[68:69] op_sel_hi:[1,0] neg_lo:[0,1] neg_hi:[0,1]
	v_mov_b32_e32 v72, v70
	v_mov_b32_e32 v74, v70
	s_nop 1
	v_permlane16_swap_b32_e32 v72, v74
	s_nop 1
	v_pk_mul_f32 v[64:65], v[64:65], v[74:75] op_sel_hi:[1,0]
	v_pk_mul_f32 v[62:63], v[62:63], v[74:75] op_sel_hi:[1,0]
	v_pk_mul_f32 v[60:61], v[60:61], v[72:73] op_sel_hi:[1,0]
	v_pk_mul_f32 v[58:59], v[58:59], v[72:73] op_sel_hi:[1,0]
	v_pk_mul_f32 v[56:57], v[56:57], v[74:75] op_sel_hi:[1,0]
	v_pk_mul_f32 v[54:55], v[54:55], v[74:75] op_sel_hi:[1,0]
	v_pk_mul_f32 v[52:53], v[52:53], v[72:73] op_sel_hi:[1,0]
	v_pk_mul_f32 v[50:51], v[50:51], v[72:73] op_sel_hi:[1,0]
	v_pk_mul_f32 v[48:49], v[48:49], v[74:75] op_sel_hi:[1,0]
	v_pk_mul_f32 v[46:47], v[46:47], v[74:75] op_sel_hi:[1,0]
	v_pk_mul_f32 v[44:45], v[44:45], v[72:73] op_sel_hi:[1,0]
	v_pk_mul_f32 v[42:43], v[42:43], v[72:73] op_sel_hi:[1,0]
	v_pk_mul_f32 v[40:41], v[40:41], v[74:75] op_sel_hi:[1,0]
	v_pk_mul_f32 v[38:39], v[38:39], v[74:75] op_sel_hi:[1,0]
	v_pk_mul_f32 v[36:37], v[36:37], v[72:73] op_sel_hi:[1,0]
	v_pk_mul_f32 v[34:35], v[34:35], v[72:73] op_sel_hi:[1,0]
	v_pk_mul_f32 v[32:33], v[32:33], v[74:75] op_sel_hi:[1,0]
	v_pk_mul_f32 v[30:31], v[30:31], v[74:75] op_sel_hi:[1,0]
	v_pk_mul_f32 v[28:29], v[28:29], v[72:73] op_sel_hi:[1,0]
	v_pk_mul_f32 v[26:27], v[26:27], v[72:73] op_sel_hi:[1,0]
	v_pk_mul_f32 v[24:25], v[24:25], v[74:75] op_sel_hi:[1,0]
	v_pk_mul_f32 v[22:23], v[22:23], v[74:75] op_sel_hi:[1,0]
	v_pk_mul_f32 v[20:21], v[20:21], v[72:73] op_sel_hi:[1,0]
	v_pk_mul_f32 v[18:19], v[18:19], v[72:73] op_sel_hi:[1,0]
	v_pk_mul_f32 v[16:17], v[16:17], v[74:75] op_sel_hi:[1,0]
	v_pk_mul_f32 v[14:15], v[14:15], v[74:75] op_sel_hi:[1,0]
	v_pk_mul_f32 v[12:13], v[12:13], v[72:73] op_sel_hi:[1,0]
	v_pk_mul_f32 v[10:11], v[10:11], v[72:73] op_sel_hi:[1,0]
	v_pk_mul_f32 v[8:9], v[8:9], v[74:75] op_sel_hi:[1,0]
	v_pk_mul_f32 v[6:7], v[6:7], v[74:75] op_sel_hi:[1,0]
	v_pk_mul_f32 v[4:5], v[4:5], v[72:73] op_sel_hi:[1,0]
	v_pk_mul_f32 v[2:3], v[2:3], v[72:73] op_sel_hi:[1,0]
	v_pk_add_f32 v[82:83], v[82:83], v[68:69] op_sel_hi:[1,0] neg_lo:[0,1] neg_hi:[0,1]
	v_pk_add_f32 v[100:101], v[100:101], v[68:69] op_sel_hi:[1,0] neg_lo:[0,1] neg_hi:[0,1]
	v_pk_add_f32 v[84:85], v[84:85], v[68:69] op_sel_hi:[1,0] neg_lo:[0,1] neg_hi:[0,1]
; #define ALAS __attribute__((address_space(3)))
; template <bool WIN> ...
;     ...
;                 for (int r = 0; r < 16; ++r) { s0[r] -= dl; s1[r] -= dl; cvec[r] = cbase - m_ref; }
;             }
;             float ls0 = 0.f, ls1 = 0.f;
;     ...
;             union PFU { u32x4 u; bf16x8 b; };
;             PFU p0, p1, p2, p3;
;             AT_EXP(s0, 0, p0);
; #pragma unroll
;             for (int kk = 0; kk < 2; ++kk)
; #pragma unroll
;                 for (int db = 0; db < NDB; ++db) vc[kk * NDB + db] = *(const ALAS bf16x8*)(sb + vx[kk + 2] + db * 4096);
;             __builtin_amdgcn_sched_barrier(0);
; #pragma unroll
;             for (int db = 0; db < NDB; ++db) o[db] = __builtin_amdgcn_mfma_f32_32x32x16_bf16(va[db], p0.b, o[db], 0, 0, 0);
;             AT_EXP(s0, 8, p1);
;             __builtin_amdgcn_sched_barrier(0);
; #pragma unroll
;             for (int db = 0; db < NDB; ++db) o[db] = __builtin_amdgcn_mfma_f32_32x32x16_bf16(va[NDB + db], p1.b, o[db], 0, 0, 0);
;             AT_EXP(s1, 0, p2);
;             __builtin_amdgcn_sched_barrier(0);
; #pragma unroll
;             for (int db = 0; db < NDB; ++db) o[db] = __builtin_amdgcn_mfma_f32_32x32x16_bf16(vc[db], p2.b, o[db], 0, 0, 0);
;             AT_EXP(s1, 8, p3);
;             __builtin_amdgcn_sched_barrier(0);
; #pragma unroll
;             for (int db = 0; db < NDB; ++db) o[db] = __builtin_amdgcn_mfma_f32_32x32x16_bf16(vc[NDB + db], p3.b, o[db], 0, 0, 0);
	v_pk_add_f32 v[102:103], v[102:103], v[68:69] op_sel_hi:[1,0] neg_lo:[0,1] neg_hi:[0,1]
	v_pk_add_f32 v[86:87], v[86:87], v[68:69] op_sel_hi:[1,0] neg_lo:[0,1] neg_hi:[0,1]
	v_pk_add_f32 v[104:105], v[104:105], v[68:69] op_sel_hi:[1,0] neg_lo:[0,1] neg_hi:[0,1]
	v_pk_add_f32 v[88:89], v[88:89], v[68:69] op_sel_hi:[1,0] neg_lo:[0,1] neg_hi:[0,1]
	v_pk_add_f32 v[106:107], v[106:107], v[68:69] op_sel_hi:[1,0] neg_lo:[0,1] neg_hi:[0,1]
	v_pk_add_f32 v[90:91], v[90:91], v[68:69] op_sel_hi:[1,0] neg_lo:[0,1] neg_hi:[0,1]
	v_pk_add_f32 v[108:109], v[108:109], v[68:69] op_sel_hi:[1,0] neg_lo:[0,1] neg_hi:[0,1]
	v_pk_add_f32 v[92:93], v[92:93], v[68:69] op_sel_hi:[1,0] neg_lo:[0,1] neg_hi:[0,1]
	v_pk_add_f32 v[110:111], v[110:111], v[68:69] op_sel_hi:[1,0] neg_lo:[0,1] neg_hi:[0,1]
	v_pk_add_f32 v[94:95], v[94:95], v[68:69] op_sel_hi:[1,0] neg_lo:[0,1] neg_hi:[0,1]
	v_pk_add_f32 v[112:113], v[112:113], v[68:69] op_sel_hi:[1,0] neg_lo:[0,1] neg_hi:[0,1]
	v_pk_add_f32 v[96:97], v[96:97], v[68:69] op_sel_hi:[1,0] neg_lo:[0,1] neg_hi:[0,1]
	v_mul_f32_e32 v0, v0, v70
	v_mov_b32_e32 v67, v66
	v_mov_b32_e32 v68, v66
	v_mov_b32_e32 v69, v66
	v_mov_b32_e32 v70, v66
	v_mov_b32_e32 v71, v66
	v_mov_b32_e32 v72, v66
	v_mov_b32_e32 v73, v66
	v_mov_b32_e32 v74, v66
	v_mov_b32_e32 v75, v66
	v_mov_b32_e32 v76, v66
	v_mov_b32_e32 v77, v66
	v_mov_b32_e32 v78, v66
	v_mov_b32_e32 v79, v66
	v_mov_b32_e32 v80, v66
	v_mov_b32_e32 v81, v66
	s_branch .LSPp_pure
.LSPp_pv:
	s_cmp_eq_u32 s86, 0
	s_cbranch_scc1 .LSPp_pure
	v_mov_b32_e32 v228, 0
	v_mov_b32_e32 v229, 0
	s_waitcnt lgkmcnt(4)
	v_mfma_f32_16x16x32_bf16 v[2:5], v[146:149], v[238:241], v[2:5]
	v_exp_f32_e32 v98, v98
	v_mfma_f32_16x16x32_bf16 v[6:9], v[146:149], v[242:245], v[6:9]
	v_exp_f32_e32 v99, v99
	v_add_f32_e32 v229, v229, v98
	v_mfma_f32_16x16x32_bf16 v[10:13], v[150:153], v[238:241], v[10:13]
	v_exp_f32_e32 v100, v100
	v_add_f32_e32 v228, v228, v99
	v_mfma_f32_16x16x32_bf16 v[14:17], v[150:153], v[242:245], v[14:17]
	v_exp_f32_e32 v101, v101
	v_add_f32_e32 v229, v229, v100
	v_mfma_f32_16x16x32_bf16 v[18:21], v[154:157], v[238:241], v[18:21]
	v_exp_f32_e32 v102, v102
	v_add_f32_e32 v228, v228, v101
	v_mfma_f32_16x16x32_bf16 v[22:25], v[154:157], v[242:245], v[22:25]
	v_exp_f32_e32 v103, v103
	v_add_f32_e32 v229, v229, v102
	v_mfma_f32_16x16x32_bf16 v[26:29], v[158:161], v[238:241], v[26:29]
	v_exp_f32_e32 v104, v104
	v_add_f32_e32 v228, v228, v103
	v_mfma_f32_16x16x32_bf16 v[30:33], v[158:161], v[242:245], v[30:33]
	v_exp_f32_e32 v105, v105
	v_add_f32_e32 v229, v229, v104
	v_add_u32_e32 v236, s99, v181
	ds_read_b128 v[146:149], v236 offset:16384
	ds_read_b128 v[150:153], v236 offset:18432
	ds_read_b128 v[154:157], v236 offset:20480
	ds_read_b128 v[158:161], v236 offset:22528
	s_waitcnt lgkmcnt(4)
	v_mfma_f32_16x16x32_bf16 v[34:37], v[130:133], v[238:241], v[34:37]
	v_exp_f32_e32 v106, v106
	v_add_f32_e32 v228, v228, v105
	v_mfma_f32_16x16x32_bf16 v[38:41], v[130:133], v[242:245], v[38:41]
	v_exp_f32_e32 v107, v107
	v_add_f32_e32 v229, v229, v106
	v_mfma_f32_16x16x32_bf16 v[42:45], v[134:137], v[238:241], v[42:45]
	v_exp_f32_e32 v108, v108
	v_add_f32_e32 v228, v228, v107
	v_mfma_f32_16x16x32_bf16 v[46:49], v[134:137], v[242:245], v[46:49]
	v_exp_f32_e32 v109, v109
	v_add_f32_e32 v229, v229, v108
	v_mfma_f32_16x16x32_bf16 v[50:53], v[138:141], v[238:241], v[50:53]
	v_exp_f32_e32 v110, v110
	v_add_f32_e32 v228, v228, v109
	v_mfma_f32_16x16x32_bf16 v[54:57], v[138:141], v[242:245], v[54:57]
	v_exp_f32_e32 v111, v111
	v_add_f32_e32 v229, v229, v110
	v_mfma_f32_16x16x32_bf16 v[58:61], v[142:145], v[238:241], v[58:61]
	v_exp_f32_e32 v112, v112
	v_add_f32_e32 v228, v228, v111
	v_mfma_f32_16x16x32_bf16 v[62:65], v[142:145], v[242:245], v[62:65]
	v_exp_f32_e32 v113, v113
	v_add_f32_e32 v229, v229, v112
	v_add_u32_e32 v237, s99, v181
	ds_read_b128 v[130:133], v237 offset:24576
	ds_read_b128 v[134:137], v237 offset:26624
	ds_read_b128 v[138:141], v237 offset:28672
	ds_read_b128 v[142:145], v237 offset:30720
	s_waitcnt lgkmcnt(4)
	v_mfma_f32_16x16x32_bf16 v[2:5], v[146:149], v[246:249], v[2:5]
	v_exp_f32_e32 v82, v82
	v_add_f32_e32 v228, v228, v113
	v_cvt_pk_bf16_f32 v238, v98, v99
	v_mfma_f32_16x16x32_bf16 v[6:9], v[146:149], v[250:253], v[6:9]
	v_exp_f32_e32 v83, v83
	v_add_f32_e32 v229, v229, v82
	v_cvt_pk_bf16_f32 v239, v100, v101
	v_mfma_f32_16x16x32_bf16 v[10:13], v[150:153], v[246:249], v[10:13]
	v_exp_f32_e32 v84, v84
	v_add_f32_e32 v228, v228, v83
	v_cvt_pk_bf16_f32 v240, v102, v103
	v_mfma_f32_16x16x32_bf16 v[14:17], v[150:153], v[250:253], v[14:17]
	v_exp_f32_e32 v85, v85
	v_add_f32_e32 v229, v229, v84
	v_cvt_pk_bf16_f32 v241, v104, v105
	v_mfma_f32_16x16x32_bf16 v[18:21], v[154:157], v[246:249], v[18:21]
	v_exp_f32_e32 v86, v86
	v_add_f32_e32 v228, v228, v85
	v_cvt_pk_bf16_f32 v242, v106, v107
	v_mfma_f32_16x16x32_bf16 v[22:25], v[154:157], v[250:253], v[22:25]
	v_exp_f32_e32 v87, v87
	v_add_f32_e32 v229, v229, v86
	v_cvt_pk_bf16_f32 v243, v108, v109
	v_mfma_f32_16x16x32_bf16 v[26:29], v[158:161], v[246:249], v[26:29]
	v_exp_f32_e32 v88, v88
	v_add_f32_e32 v228, v228, v87
	v_cvt_pk_bf16_f32 v244, v110, v111
	v_mfma_f32_16x16x32_bf16 v[30:33], v[158:161], v[250:253], v[30:33]
	v_exp_f32_e32 v89, v89
	v_add_f32_e32 v229, v229, v88
	v_cvt_pk_bf16_f32 v245, v112, v113
	s_waitcnt lgkmcnt(0)
; #define ALAS __attribute__((address_space(3)))
; template <bool WIN> ...
;     ...
;             float ls0 = 0.f, ls1 = 0.f;
;     ...
;             union PFU { u32x4 u; bf16x8 b; };
;             PFU p0, p1, p2, p3;
;             AT_EXP(s0, 0, p0);
; #pragma unroll
;             for (int kk = 0; kk < 2; ++kk)
; #pragma unroll
;                 for (int db = 0; db < NDB; ++db) vc[kk * NDB + db] = *(const ALAS bf16x8*)(sb + vx[kk + 2] + db * 4096);
;             __builtin_amdgcn_sched_barrier(0);
; #pragma unroll
;             for (int db = 0; db < NDB; ++db) o[db] = __builtin_amdgcn_mfma_f32_32x32x16_bf16(va[db], p0.b, o[db], 0, 0, 0);
;             AT_EXP(s0, 8, p1);
;             __builtin_amdgcn_sched_barrier(0);
; #pragma unroll
;             for (int db = 0; db < NDB; ++db) o[db] = __builtin_amdgcn_mfma_f32_32x32x16_bf16(va[NDB + db], p1.b, o[db], 0, 0, 0);
;             AT_EXP(s1, 0, p2);
;             __builtin_amdgcn_sched_barrier(0);
; #pragma unroll
;             for (int db = 0; db < NDB; ++db) o[db] = __builtin_amdgcn_mfma_f32_32x32x16_bf16(vc[db], p2.b, o[db], 0, 0, 0);
;             AT_EXP(s1, 8, p3);
;             __builtin_amdgcn_sched_barrier(0);
; #pragma unroll
;             for (int db = 0; db < NDB; ++db) o[db] = __builtin_amdgcn_mfma_f32_32x32x16_bf16(vc[NDB + db], p3.b, o[db], 0, 0, 0);
;             __builtin_amdgcn_sched_barrier(0);
;     ...
;             l_run += ls0 + ls1;
	v_mfma_f32_16x16x32_bf16 v[34:37], v[130:133], v[246:249], v[34:37]
	v_exp_f32_e32 v90, v90
	v_add_f32_e32 v228, v228, v89
	v_mfma_f32_16x16x32_bf16 v[38:41], v[130:133], v[250:253], v[38:41]
	v_exp_f32_e32 v91, v91
	v_add_f32_e32 v229, v229, v90
	v_mfma_f32_16x16x32_bf16 v[42:45], v[134:137], v[246:249], v[42:45]
	v_exp_f32_e32 v92, v92
	v_add_f32_e32 v228, v228, v91
	v_mfma_f32_16x16x32_bf16 v[46:49], v[134:137], v[250:253], v[46:49]
	v_exp_f32_e32 v93, v93
	v_add_f32_e32 v229, v229, v92
	v_mfma_f32_16x16x32_bf16 v[50:53], v[138:141], v[246:249], v[50:53]
	v_exp_f32_e32 v94, v94
	v_add_f32_e32 v228, v228, v93
	v_mfma_f32_16x16x32_bf16 v[54:57], v[138:141], v[250:253], v[54:57]
	v_exp_f32_e32 v95, v95
	v_add_f32_e32 v229, v229, v94
	v_mfma_f32_16x16x32_bf16 v[58:61], v[142:145], v[246:249], v[58:61]
	v_exp_f32_e32 v96, v96
	v_add_f32_e32 v228, v228, v95
	v_mfma_f32_16x16x32_bf16 v[62:65], v[142:145], v[250:253], v[62:65]
	v_exp_f32_e32 v97, v97
	v_add_f32_e32 v229, v229, v96
	v_add_f32_e32 v228, v228, v97
	v_cvt_pk_bf16_f32 v246, v82, v83
	v_cvt_pk_bf16_f32 v247, v84, v85
	v_cvt_pk_bf16_f32 v248, v86, v87
	v_cvt_pk_bf16_f32 v249, v88, v89
	v_cvt_pk_bf16_f32 v250, v90, v91
	v_cvt_pk_bf16_f32 v251, v92, v93
	v_cvt_pk_bf16_f32 v252, v94, v95
	v_cvt_pk_bf16_f32 v253, v96, v97
	s_nop 1
	v_permlane16_swap_b32_e32 v238, v242
	v_permlane16_swap_b32_e32 v239, v243
	v_permlane16_swap_b32_e32 v240, v244
	v_permlane16_swap_b32_e32 v241, v245
	v_permlane16_swap_b32_e32 v246, v250
	v_permlane16_swap_b32_e32 v247, v251
	v_permlane16_swap_b32_e32 v248, v252
	v_permlane16_swap_b32_e32 v249, v253
	v_add_f32_e32 v228, v228, v229
	s_add_i32 s86, s86, 1
	s_add_i32 s85, s85, 0x8000
	s_addk_i32 s84, 0x100
	s_add_i32 s83, s83, 64
	s_sub_i32 s82, s82, 64
	v_add_f32_e32 v0, v0, v228
	v_lshl_add_u64 v[172:173], v[172:173], 0, s[48:49]
	s_cmpk_eq_u32 s84, 0x8000
	v_lshl_add_u64 v[174:175], v[174:175], 0, s[60:61]
	s_cbranch_scc0 .LSPp_top
	s_branch .LSPp_exit
.LSPp_pure:
	v_exp_f32_e32 v98, v98
	v_exp_f32_e32 v99, v99
	v_exp_f32_e32 v100, v100
	v_exp_f32_e32 v101, v101
	v_exp_f32_e32 v102, v102
	v_exp_f32_e32 v103, v103
	v_exp_f32_e32 v104, v104
	v_exp_f32_e32 v105, v105
	v_cvt_pk_bf16_f32 v238, v98, v99
	v_cvt_pk_bf16_f32 v239, v100, v101
	v_cvt_pk_bf16_f32 v240, v102, v103
	v_cvt_pk_bf16_f32 v241, v104, v105
	v_mov_b32_e32 v228, v98
	v_mov_b32_e32 v229, v102
	v_add_f32_e32 v228, v228, v99
	v_add_f32_e32 v229, v229, v103
	v_add_f32_e32 v228, v228, v100
	v_add_f32_e32 v229, v229, v104
	v_add_f32_e32 v228, v228, v101
	v_add_f32_e32 v229, v229, v105
	v_exp_f32_e32 v106, v106
	v_exp_f32_e32 v107, v107
	v_exp_f32_e32 v108, v108
	v_exp_f32_e32 v109, v109
	v_exp_f32_e32 v110, v110
	v_exp_f32_e32 v111, v111
	v_exp_f32_e32 v112, v112
	v_exp_f32_e32 v113, v113
	v_cvt_pk_bf16_f32 v242, v106, v107
	v_cvt_pk_bf16_f32 v243, v108, v109
	v_cvt_pk_bf16_f32 v244, v110, v111
	v_cvt_pk_bf16_f32 v245, v112, v113
	v_add_f32_e32 v228, v228, v106
	v_add_f32_e32 v229, v229, v110
	v_add_f32_e32 v228, v228, v107
	v_add_f32_e32 v229, v229, v111
	v_add_f32_e32 v228, v228, v108
	v_add_f32_e32 v229, v229, v112
	v_add_f32_e32 v228, v228, v109
	v_add_f32_e32 v229, v229, v113
	v_exp_f32_e32 v82, v82
	v_exp_f32_e32 v83, v83
	v_exp_f32_e32 v84, v84
	v_exp_f32_e32 v85, v85
	v_exp_f32_e32 v86, v86
	v_exp_f32_e32 v87, v87
	v_exp_f32_e32 v88, v88
	v_exp_f32_e32 v89, v89
	v_cvt_pk_bf16_f32 v246, v82, v83
	v_cvt_pk_bf16_f32 v247, v84, v85
	v_cvt_pk_bf16_f32 v248, v86, v87
	v_cvt_pk_bf16_f32 v249, v88, v89
	v_add_f32_e32 v228, v228, v82
	v_add_f32_e32 v229, v229, v86
	v_add_f32_e32 v228, v228, v83
	v_add_f32_e32 v229, v229, v87
	v_add_f32_e32 v228, v228, v84
	v_add_f32_e32 v229, v229, v88
	v_add_f32_e32 v228, v228, v85
	v_add_f32_e32 v229, v229, v89
	v_exp_f32_e32 v90, v90
	v_exp_f32_e32 v91, v91
	v_exp_f32_e32 v92, v92
	v_exp_f32_e32 v93, v93
	v_exp_f32_e32 v94, v94
	v_exp_f32_e32 v95, v95
	v_exp_f32_e32 v96, v96
	v_exp_f32_e32 v97, v97
	v_cvt_pk_bf16_f32 v250, v90, v91
	v_cvt_pk_bf16_f32 v251, v92, v93
	v_cvt_pk_bf16_f32 v252, v94, v95
	v_cvt_pk_bf16_f32 v253, v96, v97
	v_add_f32_e32 v228, v228, v90
	v_add_f32_e32 v229, v229, v94
	v_add_f32_e32 v228, v228, v91
	v_add_f32_e32 v229, v229, v95
	v_add_f32_e32 v228, v228, v92
	v_add_f32_e32 v229, v229, v96
	v_add_f32_e32 v228, v228, v93
	v_add_f32_e32 v229, v229, v97
	s_nop 1
	v_permlane16_swap_b32_e32 v238, v242
	v_permlane16_swap_b32_e32 v239, v243
	v_permlane16_swap_b32_e32 v240, v244
	v_permlane16_swap_b32_e32 v241, v245
	v_permlane16_swap_b32_e32 v246, v250
	v_permlane16_swap_b32_e32 v247, v251
	v_permlane16_swap_b32_e32 v248, v252
	v_permlane16_swap_b32_e32 v249, v253
	v_add_f32_e32 v228, v228, v229
	s_add_i32 s86, s86, 1
	s_add_i32 s85, s85, 0x8000
	s_addk_i32 s84, 0x100
	s_add_i32 s83, s83, 64
	s_sub_i32 s82, s82, 64
	v_add_f32_e32 v0, v0, v228
	v_lshl_add_u64 v[172:173], v[172:173], 0, s[48:49]
	s_cmpk_eq_u32 s84, 0x8000
	v_lshl_add_u64 v[174:175], v[174:175], 0, s[60:61]
	s_cbranch_scc0 .LSPp_top
	s_branch .LSPp_exit
; template <bool WIN> ...
;     ...
;             for (int db = 0; db < NDB; ++db) o[db] = __builtin_amdgcn_mfma_f32_32x32x16_bf16(va[db], p0.b, o[db], 0, 0, 0);
;             AT_EXP(s0, 8, p1);
;             __builtin_amdgcn_sched_barrier(0);
; #pragma unroll
;             for (int db = 0; db < NDB; ++db) o[db] = __builtin_amdgcn_mfma_f32_32x32x16_bf16(va[NDB + db], p1.b, o[db], 0, 0, 0);
;             AT_EXP(s1, 0, p2);
;             __builtin_amdgcn_sched_barrier(0);
; #pragma unroll
;             for (int db = 0; db < NDB; ++db) o[db] = __builtin_amdgcn_mfma_f32_32x32x16_bf16(vc[db], p2.b, o[db], 0, 0, 0);
;             AT_EXP(s1, 8, p3);
;             __builtin_amdgcn_sched_barrier(0);
; #pragma unroll
;             for (int db = 0; db < NDB; ++db) o[db] = __builtin_amdgcn_mfma_f32_32x32x16_bf16(vc[NDB + db], p3.b, o[db], 0, 0, 0);
.LSPp_exit:
	s_add_i32 s99, s85, 0xfffe8000
	s_and_b32 s99, s99, 0x18000
	v_add_u32_e32 v236, s99, v179
	ds_read_b128 v[146:149], v236 offset:16384
	ds_read_b128 v[150:153], v236 offset:18432
	ds_read_b128 v[154:157], v236 offset:20480
	ds_read_b128 v[158:161], v236 offset:22528
	v_add_u32_e32 v237, s99, v179
	ds_read_b128 v[130:133], v237 offset:24576
	ds_read_b128 v[134:137], v237 offset:26624
	ds_read_b128 v[138:141], v237 offset:28672
	ds_read_b128 v[142:145], v237 offset:30720
	s_waitcnt lgkmcnt(4)
	v_mfma_f32_16x16x32_bf16 v[2:5], v[146:149], v[238:241], v[2:5]
	v_mfma_f32_16x16x32_bf16 v[6:9], v[146:149], v[242:245], v[6:9]
	v_mfma_f32_16x16x32_bf16 v[10:13], v[150:153], v[238:241], v[10:13]
	v_mfma_f32_16x16x32_bf16 v[14:17], v[150:153], v[242:245], v[14:17]
	v_mfma_f32_16x16x32_bf16 v[18:21], v[154:157], v[238:241], v[18:21]
	v_mfma_f32_16x16x32_bf16 v[22:25], v[154:157], v[242:245], v[22:25]
	v_mfma_f32_16x16x32_bf16 v[26:29], v[158:161], v[238:241], v[26:29]
	v_mfma_f32_16x16x32_bf16 v[30:33], v[158:161], v[242:245], v[30:33]
	v_add_u32_e32 v236, s99, v181
	ds_read_b128 v[146:149], v236 offset:16384
	ds_read_b128 v[150:153], v236 offset:18432
	ds_read_b128 v[154:157], v236 offset:20480
	ds_read_b128 v[158:161], v236 offset:22528
	s_waitcnt lgkmcnt(4)
	v_mfma_f32_16x16x32_bf16 v[34:37], v[130:133], v[238:241], v[34:37]
	v_mfma_f32_16x16x32_bf16 v[38:41], v[130:133], v[242:245], v[38:41]
	v_mfma_f32_16x16x32_bf16 v[42:45], v[134:137], v[238:241], v[42:45]
	v_mfma_f32_16x16x32_bf16 v[46:49], v[134:137], v[242:245], v[46:49]
	v_mfma_f32_16x16x32_bf16 v[50:53], v[138:141], v[238:241], v[50:53]
	v_mfma_f32_16x16x32_bf16 v[54:57], v[138:141], v[242:245], v[54:57]
	v_mfma_f32_16x16x32_bf16 v[58:61], v[142:145], v[238:241], v[58:61]
	v_mfma_f32_16x16x32_bf16 v[62:65], v[142:145], v[242:245], v[62:65]
	v_add_u32_e32 v237, s99, v181
	ds_read_b128 v[130:133], v237 offset:24576
	ds_read_b128 v[134:137], v237 offset:26624
	ds_read_b128 v[138:141], v237 offset:28672
	ds_read_b128 v[142:145], v237 offset:30720
	s_waitcnt lgkmcnt(4)
	v_mfma_f32_16x16x32_bf16 v[2:5], v[146:149], v[246:249], v[2:5]
	v_mfma_f32_16x16x32_bf16 v[6:9], v[146:149], v[250:253], v[6:9]
	v_mfma_f32_16x16x32_bf16 v[10:13], v[150:153], v[246:249], v[10:13]
	v_mfma_f32_16x16x32_bf16 v[14:17], v[150:153], v[250:253], v[14:17]
	v_mfma_f32_16x16x32_bf16 v[18:21], v[154:157], v[246:249], v[18:21]
	v_mfma_f32_16x16x32_bf16 v[22:25], v[154:157], v[250:253], v[22:25]
	v_mfma_f32_16x16x32_bf16 v[26:29], v[158:161], v[246:249], v[26:29]
	v_mfma_f32_16x16x32_bf16 v[30:33], v[158:161], v[250:253], v[30:33]
	s_waitcnt lgkmcnt(0)
	v_mfma_f32_16x16x32_bf16 v[34:37], v[130:133], v[246:249], v[34:37]
	v_mfma_f32_16x16x32_bf16 v[38:41], v[130:133], v[250:253], v[38:41]
	v_mfma_f32_16x16x32_bf16 v[42:45], v[134:137], v[246:249], v[42:45]
	v_mfma_f32_16x16x32_bf16 v[46:49], v[134:137], v[250:253], v[46:49]
	v_mfma_f32_16x16x32_bf16 v[50:53], v[138:141], v[246:249], v[50:53]
	v_mfma_f32_16x16x32_bf16 v[54:57], v[138:141], v[250:253], v[54:57]
	v_mfma_f32_16x16x32_bf16 v[58:61], v[142:145], v[246:249], v[58:61]
	v_mfma_f32_16x16x32_bf16 v[62:65], v[142:145], v[250:253], v[62:65]
	s_branch .LBB0_262

; __device__ __forceinline__ unsigned cvt_pk_bf16(float lo, float hi) { unsigned r; asm volatile("v_cvt_pk_bf16_f32 %0, %1, %2" : "=v"(r) : "v"(lo), "v"(hi)); return r; }
; #define ALAS __attribute__((address_space(3)))
; template <bool WIN> ...
;     ...
;     asm volatile("s_waitcnt lgkmcnt(0)\n\ts_barrier" ::: "memory");
;     ...
;     const float l_tot = l_run + __shfl_xor(l_run, 32);
;     const float inv = 1.0f / l_tot;
;     const size_t orow = (size_t)(seq_base + qw + l31) * 1024;
;     if (WIN) {
;         bf16_t* yp = Y + orow + (2 * hsel + half) * 64 + 8 * hi;
; #pragma unroll
;         for (int db = 0; db < NDB; ++db)
; #pragma unroll
;             for (int p = 0; p < 2; ++p) {
;                 u32x2 w0, w1;
;                 w0.x = cvt_pk_bf16(o[db][8 * p] * inv, o[db][8 * p + 1] * inv); w0.y = cvt_pk_bf16(o[db][8 * p + 2] * inv, o[db][8 * p + 3] * inv);
;                 w1.x = cvt_pk_bf16(o[db][8 * p + 4] * inv, o[db][8 * p + 5] * inv); w1.y = cvt_pk_bf16(o[db][8 * p + 6] * inv, o[db][8 * p + 7] * inv);
;                 const u32x2 snd = hi ? w0 : w1, mine = hi ? w1 : w0;
;                 u32x2 rcv; rcv.x = (unsigned)__shfl_xor((int)snd.x, 32); rcv.y = (unsigned)__shfl_xor((int)snd.y, 32);
;                 u32x4 ow; if (hi) { ow.x = rcv.x; ow.y = rcv.y; ow.z = mine.x; ow.w = mine.y; } else { ow.x = mine.x; ow.y = mine.y; ow.z = rcv.x; ow.w = rcv.y; }
;                 *(u32x4*)(yp + 32 * db + 16 * p) = ow;
;             }
;     } else {
;         ALAS f32x4* xch = (ALAS f32x4*)lds + (size_t)wq * 1024 + l31;
.LBB0_262:
	ds_bpermute_b32 v66, v176, v0
	s_waitcnt lgkmcnt(0)
	s_barrier
	s_nop 7
	v_mbcnt_lo_u32_b32 v82, -1, 0
	v_mbcnt_hi_u32_b32 v82, -1, v82
	v_and_b32_e32 v83, 15, v82
	v_lshrrev_b32_e32 v84, 4, v82
	v_and_b32_e32 v85, 2, v84
	v_lshrrev_b32_e32 v86, 1, v84
	v_xor_b32_e32 v86, v86, v84
	v_and_b32_e32 v86, 1, v86
	v_xor_b32_e32 v86, 1, v86
	v_lshlrev_b32_e32 v86, 3, v86
	s_add_i32 s98, s20, 0x1000
	s_and_b32 s98, s98, 0x1c00
	s_lshl_b32 s98, s98, 4
	v_lshl_add_u32 v87, v83, 9, v86
	v_add_u32_e32 v87, s98, v87
	v_add_u32_e32 v88, 0x2000, v87
	v_xor_b32_e32 v89, v85, v83
	v_lshlrev_b32_e32 v89, 4, v89
	v_xor_b32_e32 v90, 0x100, v89
	v_xor_b32_e32 v91, 0x0, v89
	v_add_u32_e32 v91, v87, v91
	ds_write_b64 v91, v[2:3]
	v_xor_b32_e32 v91, 0x10, v89
	v_add_u32_e32 v91, v87, v91
	ds_write_b64 v91, v[4:5]
	v_xor_b32_e32 v91, 0x0, v90
	v_add_u32_e32 v91, v88, v91
	ds_write_b64 v91, v[6:7]
	v_xor_b32_e32 v91, 0x10, v90
	v_add_u32_e32 v91, v88, v91
	ds_write_b64 v91, v[8:9]
	v_xor_b32_e32 v91, 0x40, v89
	v_add_u32_e32 v91, v87, v91
	ds_write_b64 v91, v[10:11]
	v_xor_b32_e32 v91, 0x50, v89
	v_add_u32_e32 v91, v87, v91
	ds_write_b64 v91, v[12:13]
	v_xor_b32_e32 v91, 0x40, v90
	v_add_u32_e32 v91, v88, v91
	ds_write_b64 v91, v[14:15]
	v_xor_b32_e32 v91, 0x50, v90
	v_add_u32_e32 v91, v88, v91
	ds_write_b64 v91, v[16:17]
	s_waitcnt lgkmcnt(0)
	v_xor_b32_e32 v91, 0x80, v89
	v_add_u32_e32 v91, v87, v91
	ds_write_b64 v91, v[18:19]
	v_xor_b32_e32 v91, 0x90, v89
	v_add_u32_e32 v91, v87, v91
	ds_write_b64 v91, v[20:21]
	v_xor_b32_e32 v91, 0x80, v90
	v_add_u32_e32 v91, v88, v91
	ds_write_b64 v91, v[22:23]
	v_xor_b32_e32 v91, 0x90, v90
	v_add_u32_e32 v91, v88, v91
	ds_write_b64 v91, v[24:25]
	v_xor_b32_e32 v91, 0xc0, v89
	v_add_u32_e32 v91, v87, v91
	ds_write_b64 v91, v[26:27]
	v_xor_b32_e32 v91, 0xd0, v89
	v_add_u32_e32 v91, v87, v91
	ds_write_b64 v91, v[28:29]
	v_xor_b32_e32 v91, 0xc0, v90
	v_add_u32_e32 v91, v88, v91
	ds_write_b64 v91, v[30:31]
	v_xor_b32_e32 v91, 0xd0, v90
	v_add_u32_e32 v91, v88, v91
	ds_write_b64 v91, v[32:33]
	s_waitcnt lgkmcnt(0)
	v_xor_b32_e32 v91, 0x100, v89
	v_add_u32_e32 v91, v87, v91
	ds_write_b64 v91, v[34:35]
	v_xor_b32_e32 v91, 0x110, v89
	v_add_u32_e32 v91, v87, v91
	ds_write_b64 v91, v[36:37]
	v_xor_b32_e32 v91, 0x100, v90
	v_add_u32_e32 v91, v88, v91
	ds_write_b64 v91, v[38:39]
	v_xor_b32_e32 v91, 0x110, v90
	v_add_u32_e32 v91, v88, v91
	ds_write_b64 v91, v[40:41]
	v_xor_b32_e32 v91, 0x140, v89
	v_add_u32_e32 v91, v87, v91
	ds_write_b64 v91, v[42:43]
	v_xor_b32_e32 v91, 0x150, v89
	v_add_u32_e32 v91, v87, v91
	ds_write_b64 v91, v[44:45]
	v_xor_b32_e32 v91, 0x140, v90
	v_add_u32_e32 v91, v88, v91
	ds_write_b64 v91, v[46:47]
	v_xor_b32_e32 v91, 0x150, v90
	v_add_u32_e32 v91, v88, v91
	ds_write_b64 v91, v[48:49]
	s_waitcnt lgkmcnt(0)
	v_xor_b32_e32 v91, 0x180, v89
	v_add_u32_e32 v91, v87, v91
	ds_write_b64 v91, v[50:51]
	v_xor_b32_e32 v91, 0x190, v89
	v_add_u32_e32 v91, v87, v91
	ds_write_b64 v91, v[52:53]
	v_xor_b32_e32 v91, 0x180, v90
	v_add_u32_e32 v91, v88, v91
	ds_write_b64 v91, v[54:55]
	v_xor_b32_e32 v91, 0x190, v90
	v_add_u32_e32 v91, v88, v91
	ds_write_b64 v91, v[56:57]
	v_xor_b32_e32 v91, 0x1c0, v89
	v_add_u32_e32 v91, v87, v91
	ds_write_b64 v91, v[58:59]
	v_xor_b32_e32 v91, 0x1d0, v89
	v_add_u32_e32 v91, v87, v91
	ds_write_b64 v91, v[60:61]
	v_xor_b32_e32 v91, 0x1c0, v90
	v_add_u32_e32 v91, v88, v91
	ds_write_b64 v91, v[62:63]
	v_xor_b32_e32 v91, 0x1d0, v90
	v_add_u32_e32 v91, v88, v91
	ds_write_b64 v91, v[64:65]
	s_waitcnt lgkmcnt(0)
	v_and_b32_e32 v83, 31, v82
	v_lshrrev_b32_e32 v84, 5, v82
	v_lshlrev_b32_e32 v87, 9, v83
	v_add_u32_e32 v87, s98, v87
	v_xor_b32_e32 v89, v84, v83
	v_lshlrev_b32_e32 v89, 4, v89
	v_xor_b32_e32 v91, 0x0, v89
	v_add_u32_e32 v91, v87, v91
	ds_read_b128 v[50:53], v91
	v_xor_b32_e32 v91, 0x20, v89
	v_add_u32_e32 v91, v87, v91
	ds_read_b128 v[54:57], v91
	v_xor_b32_e32 v91, 0x40, v89
	v_add_u32_e32 v91, v87, v91
	ds_read_b128 v[58:61], v91
	v_xor_b32_e32 v91, 0x60, v89
	v_add_u32_e32 v91, v87, v91
	ds_read_b128 v[62:65], v91
	v_xor_b32_e32 v91, 0x80, v89
	v_add_u32_e32 v91, v87, v91
	ds_read_b128 v[34:37], v91
	v_xor_b32_e32 v91, 0xa0, v89
	v_add_u32_e32 v91, v87, v91
	ds_read_b128 v[38:41], v91
	v_xor_b32_e32 v91, 0xc0, v89
	v_add_u32_e32 v91, v87, v91
	ds_read_b128 v[42:45], v91
	v_xor_b32_e32 v91, 0xe0, v89
	v_add_u32_e32 v91, v87, v91
	ds_read_b128 v[46:49], v91
	s_waitcnt lgkmcnt(0)
	v_xor_b32_e32 v91, 0x100, v89
	v_add_u32_e32 v91, v87, v91
	ds_read_b128 v[18:21], v91
	v_xor_b32_e32 v91, 0x120, v89
	v_add_u32_e32 v91, v87, v91
	ds_read_b128 v[22:25], v91
	v_xor_b32_e32 v91, 0x140, v89
	v_add_u32_e32 v91, v87, v91
	ds_read_b128 v[26:29], v91
	v_xor_b32_e32 v91, 0x160, v89
	v_add_u32_e32 v91, v87, v91
	ds_read_b128 v[30:33], v91
	v_xor_b32_e32 v91, 0x180, v89
	v_add_u32_e32 v91, v87, v91
	ds_read_b128 v[2:5], v91
	v_xor_b32_e32 v91, 0x1a0, v89
	v_add_u32_e32 v91, v87, v91
	ds_read_b128 v[6:9], v91
	v_xor_b32_e32 v91, 0x1c0, v89
	v_add_u32_e32 v91, v87, v91
	ds_read_b128 v[10:13], v91
	v_xor_b32_e32 v91, 0x1e0, v89
	v_add_u32_e32 v91, v87, v91
	ds_read_b128 v[14:17], v91
	s_waitcnt lgkmcnt(0)
	v_bfe_u32 v83, v82, 1, 3
	v_xor_b32_e32 v85, v84, v83
	v_lshlrev_b32_e32 v179, 4, v85
	v_or_b32_e32 v84, 2, v84
	v_xor_b32_e32 v85, v84, v83
	v_lshlrev_b32_e32 v181, 4, v85
	v_lshl_add_u32 v67, s77, 14, v192
	s_cmp_lg_u32 s76, 1
	s_waitcnt lgkmcnt(0)
	v_add_f32_e32 v0, v0, v66
	v_div_scale_f32 v66, s[64:65], v0, v0, 1.0
	v_rcp_f32_e32 v68, v66
	v_div_scale_f32 v69, vcc, 1.0, v0, 1.0
	v_fma_f32 v70, -v66, v68, 1.0
	v_fmac_f32_e32 v68, v70, v68
	v_mul_f32_e32 v70, v69, v68
	v_fma_f32 v71, -v66, v70, v69
	v_fmac_f32_e32 v70, v71, v68
	v_fma_f32 v66, -v66, v70, v69
	v_div_fmas_f32 v66, v66, v68, v70
	v_div_fixup_f32 v162, v66, v0, 1.0
	v_add_u32_e32 v0, v67, v193
	s_cbranch_scc1 .LBB0_264
; template <bool WIN> ...
;     ...
;         if (half == 1) {
; #pragma unroll
;             for (int db = 0; db < NDB; ++db)
; #pragma unroll
;                 for (int g = 0; g < 4; ++g) { f32x4 v; v[0] = o[db][4 * g] * inv; v[1] = o[db][4 * g + 1] * inv; v[2] = o[db][4 * g + 2] * inv; v[3] = o[db][4 * g + 3] * inv;
;                     xch[(8 * db + 2 * g + hi) * 32] = v; }
;         }
	v_pk_mul_f32 v[66:67], v[50:51], v[162:163] op_sel_hi:[1,0]
	v_pk_mul_f32 v[68:69], v[52:53], v[162:163] op_sel_hi:[1,0]
	ds_write_b128 v0, v[66:69]
	v_pk_mul_f32 v[66:67], v[54:55], v[162:163] op_sel_hi:[1,0]
	v_pk_mul_f32 v[68:69], v[56:57], v[162:163] op_sel_hi:[1,0]
	ds_write_b128 v0, v[66:69] offset:1024
	v_pk_mul_f32 v[66:67], v[58:59], v[162:163] op_sel_hi:[1,0]
	v_pk_mul_f32 v[68:69], v[60:61], v[162:163] op_sel_hi:[1,0]
	ds_write_b128 v0, v[66:69] offset:2048
	v_pk_mul_f32 v[66:67], v[62:63], v[162:163] op_sel_hi:[1,0]
	v_pk_mul_f32 v[68:69], v[64:65], v[162:163] op_sel_hi:[1,0]
	ds_write_b128 v0, v[66:69] offset:3072
	v_pk_mul_f32 v[66:67], v[34:35], v[162:163] op_sel_hi:[1,0]
	v_pk_mul_f32 v[68:69], v[36:37], v[162:163] op_sel_hi:[1,0]
	ds_write_b128 v0, v[66:69] offset:4096
	v_pk_mul_f32 v[66:67], v[38:39], v[162:163] op_sel_hi:[1,0]
	v_pk_mul_f32 v[68:69], v[40:41], v[162:163] op_sel_hi:[1,0]
	ds_write_b128 v0, v[66:69] offset:5120
	v_pk_mul_f32 v[66:67], v[42:43], v[162:163] op_sel_hi:[1,0]
	v_pk_mul_f32 v[68:69], v[44:45], v[162:163] op_sel_hi:[1,0]
	ds_write_b128 v0, v[66:69] offset:6144
	v_pk_mul_f32 v[66:67], v[46:47], v[162:163] op_sel_hi:[1,0]
	v_pk_mul_f32 v[68:69], v[48:49], v[162:163] op_sel_hi:[1,0]
	ds_write_b128 v0, v[66:69] offset:7168
	v_pk_mul_f32 v[66:67], v[18:19], v[162:163] op_sel_hi:[1,0]
	v_pk_mul_f32 v[68:69], v[20:21], v[162:163] op_sel_hi:[1,0]
	ds_write_b128 v0, v[66:69] offset:8192
	v_pk_mul_f32 v[66:67], v[22:23], v[162:163] op_sel_hi:[1,0]
	v_pk_mul_f32 v[68:69], v[24:25], v[162:163] op_sel_hi:[1,0]
	ds_write_b128 v0, v[66:69] offset:9216
	v_pk_mul_f32 v[66:67], v[26:27], v[162:163] op_sel_hi:[1,0]
	v_pk_mul_f32 v[68:69], v[28:29], v[162:163] op_sel_hi:[1,0]
	ds_write_b128 v0, v[66:69] offset:10240
	v_pk_mul_f32 v[66:67], v[30:31], v[162:163] op_sel_hi:[1,0]
	v_pk_mul_f32 v[68:69], v[32:33], v[162:163] op_sel_hi:[1,0]
	ds_write_b128 v0, v[66:69] offset:11264
	v_pk_mul_f32 v[66:67], v[2:3], v[162:163] op_sel_hi:[1,0]
	v_pk_mul_f32 v[68:69], v[4:5], v[162:163] op_sel_hi:[1,0]
	ds_write_b128 v0, v[66:69] offset:12288
	v_pk_mul_f32 v[66:67], v[6:7], v[162:163] op_sel_hi:[1,0]
	v_pk_mul_f32 v[68:69], v[8:9], v[162:163] op_sel_hi:[1,0]
	ds_write_b128 v0, v[66:69] offset:13312
	v_pk_mul_f32 v[66:67], v[10:11], v[162:163] op_sel_hi:[1,0]
	v_pk_mul_f32 v[68:69], v[12:13], v[162:163] op_sel_hi:[1,0]
	ds_write_b128 v0, v[66:69] offset:14336
	v_pk_mul_f32 v[66:67], v[14:15], v[162:163] op_sel_hi:[1,0]
	v_pk_mul_f32 v[68:69], v[16:17], v[162:163] op_sel_hi:[1,0]
	ds_write_b128 v0, v[66:69] offset:15360

; template <bool WIN> ...
;     ...
;     const int tid = threadIdx.x, lane = tid & 63, l31 = lane & 31, hi = lane >> 5;
;     const int wid = __builtin_amdgcn_readfirstlane(tid >> 6), half = wid >> 2, wq = wid & 3;
;     const int qw = q0 + 32 * wq;
;     int qcol, kcol0, kcol1, vrow0, bhead;
;     if (WIN) { qcol = (2 * hsel + half) * 64; kcol0 = 512 + (hsel >> 1) * 64; kcol1 = kcol0; vrow0 = (hsel >> 1) * 64; bhead = 2 * hsel; }
;     else { qcol = 640 + (2 * hsel + half) * 64; kcol0 = 1152 + (2 * hsel) * 64; kcol1 = kcol0 + 64; vrow0 = 128 + hsel * 128; bhead = 8 + hsel; }
;     const ALAS float* lut = (const ALAS float*)(lds + OFF_LUT) + (WIN ? (bhead + half) : bhead) * LUTW;
;     const int t_lo = WIN ? (q0 >= 128 ? (q0 - 128) / 64 : 0) : 0;
;     const int t_hi = WIN ? ((q0 + 256) / 64 < S / 64 ? (q0 + 256) / 64 : S / 64) : S / 64;
;     const int NT = t_hi - t_lo;
;     const unsigned ldsb = (unsigned)(uintptr_t)lds;
;     const int drow = 8 * wid + (lane >> 3), dch = (lane & 7) ^ ((4 * wid + (lane >> 4)) & 7);
;     const bf16_t* kg = QK + ((size_t)((seq_base >> 6) + t_lo) * 26 * 64 + drow) * 64 + dch * 8 + kcol0 * 64;
;     const bf16_t* vg = VT + ((size_t)((seq_base >> 6) + t_lo) * 640 + vrow0 + drow) * 64 + dch * 8;
;     const unsigned dk = ldsb + wid * 1024;
;     ...
;     constexpr int NPW = WIN ? 2 : 4;
;     bf16x8 qfr[4];
;     { const int qrow = seq_base + qw + l31; const bf16_t* qp = QK + ((size_t)((qrow >> 6) * 26 + (qcol >> 6)) * 64 + (qrow & 63)) * 64 + hi * 8;
; #pragma unroll
;       for (int ds = 0; ds < 4; ++ds) qfr[ds] = *(const bf16x8*)(qp + ds * 16); }
;     ...
;     AT_DMA(0); if (NT > 1) AT_DMA(1); if (NT > 2) AT_DMA(2);
;     constexpr float THR = 8.0f;
;     float m_ref = WIN ? sinkp[2 * hsel + half] * LOG2E : 0.f;
;     float l_run = (WIN && hi == 0) ? 1.f : 0.f;
;     float cbase = 0.f;
;     f32x16 cvec;
; #pragma unroll
;     for (int r = 0; r < 16; ++r) cvec[r] = cbase - m_ref;
;     f32x16 o[NDB];
; #pragma unroll
;     for (int db = 0; db < NDB; ++db)
; #pragma unroll
;         for (int r = 0; r < 16; ++r) o[db][r] = 0.f;
;     const int krow = pi32(l31), fK = (krow >> 1) & 7, fV = (l31 >> 1) & 7;
;     int kx[4], vx[4];
; #pragma unroll
;     for (int c = 0; c < 4; ++c) { kx[c] = (WIN ? OFF_K0 : (half ? OFF_K1 : OFF_K0)) + krow * 128 + (((2 * c + hi) ^ fK) << 4); vx[c] = OFF_V + l31 * 128 + (((2 * c + hi) ^ fV) << 4); }
.LBB0_268:
	v_readfirstlane_b32 s33, v230
	s_lshl_b32 s26, s25, 13
	s_bfe_u32 s27, s33, 0x20006
	s_add_i32 s26, s26, s23
	s_lshl_b32 s28, s27, 5
	s_and_b32 s26, s26, 0xfffff800
	s_or_b32 s28, s28, s22
	s_add_i32 s29, s26, 0x10000
	s_lshr_b32 s26, s33, 8
	v_or_b32_e32 v10, s28, v185
	v_or_b32_e32 v170, s29, v10
	s_add_i32 s30, s26, s66
	v_ashrrev_i32_e32 v2, 6, v170
	v_mov_b32_e32 v0, s30
	v_mad_u64_u32 v[2:3], s[30:31], v2, 26, v[0:1]
	v_ashrrev_i32_e32 v3, 31, v2
	v_lshlrev_b64 v[2:3], 13, v[2:3]
	v_lshlrev_b32_e32 v0, 7, v10
	v_lshl_add_u64 v[2:3], s[6:7], 0, v[2:3]
	v_and_b32_e32 v4, 0x1f80, v0
	v_mov_b32_e32 v5, v1
	v_lshl_add_u64 v[2:3], v[2:3], 0, v[4:5]
	v_lshl_add_u64 v[2:3], v[2:3], 0, v[164:165]
	global_load_dwordx4 v[114:117], v[2:3], off offset:96
	global_load_dwordx4 v[118:121], v[2:3], off offset:64
	global_load_dwordx4 v[122:125], v[2:3], off offset:32
	global_load_dwordx4 v[126:129], v[2:3], off
	s_lshr_b32 s62, s33, 6
	s_lshr_b32 s30, s33, 4
	v_lshl_or_b32 v0, s62, 3, v188
	s_and_b32 s30, s30, 4
	s_ashr_i32 s76, s29, 6
	v_bitop3_b32 v4, s30, v186, v189 bitop3:0x36
	v_mad_i64_i32 v[2:3], s[30:31], s76, v194, v[0:1]
	v_lshlrev_b64 v[2:3], 7, v[2:3]
	v_lshl_add_u64 v[2:3], s[6:7], 0, v[2:3]
	v_lshlrev_b32_e32 v4, 4, v4
	s_mul_hi_i32 s31, s76, 0x280
	s_mul_i32 s30, s76, 0x280
	v_lshl_add_u64 v[2:3], v[2:3], 0, v[4:5]
	s_or_b64 s[30:31], s[30:31], s[12:13]
	v_lshl_add_u64 v[2:3], v[2:3], 0, s[18:19]
	v_lshl_add_u64 v[6:7], s[30:31], 0, v[0:1]
	s_lshl_b32 s29, s62, 10
	v_lshlrev_b64 v[6:7], 7, v[6:7]
	v_lshl_add_u64 v[8:9], v[2:3], 0, s[36:37]
	s_add_i32 s29, s29, 0
	s_mov_b32 s30, m0
	s_mov_b32 m0, s29
	s_nop 0
	global_load_lds_dwordx4 v[8:9], off
	s_mov_b32 m0, s30
	v_lshl_add_u64 v[6:7], s[4:5], 0, v[6:7]
	v_lshl_add_u64 v[8:9], v[2:3], 0, s[38:39]
	s_add_i32 s30, s29, 0x2000
	s_mov_b32 s31, m0
	s_mov_b32 m0, s30
	s_nop 0
	global_load_lds_dwordx4 v[8:9], off
	s_mov_b32 m0, s31
	v_lshl_add_u64 v[6:7], v[6:7], 0, v[4:5]
	s_add_i32 s30, s29, 0x4000
	s_mov_b32 s31, m0
	s_mov_b32 m0, s30
	s_nop 0
	global_load_lds_dwordx4 v[6:7], off
	s_mov_b32 m0, s31
	v_lshl_add_u64 v[8:9], v[6:7], 0, s[40:41]
	s_add_i32 s30, s29, 0x6000
	s_mov_b32 s31, m0
	s_mov_b32 m0, s30
	s_nop 0
	global_load_lds_dwordx4 v[8:9], off
	s_mov_b32 m0, s31
	s_add_i32 s30, s29, 0x8000
	v_lshl_add_u64 v[8:9], v[2:3], 0, s[42:43]
	s_mov_b32 s31, m0
	s_mov_b32 m0, s30
	s_nop 0
	global_load_lds_dwordx4 v[8:9], off
	s_mov_b32 m0, s31
	v_lshl_add_u64 v[8:9], v[2:3], 0, s[46:47]
	s_add_i32 s30, s29, 0xa000
	s_mov_b32 s31, m0
	s_mov_b32 m0, s30
	s_nop 0
	global_load_lds_dwordx4 v[8:9], off
	s_mov_b32 m0, s31
	v_lshl_add_u64 v[8:9], v[6:7], 0, s[48:49]
	s_add_i32 s30, s29, 0xc000
	s_mov_b32 s31, m0
	s_mov_b32 m0, s30
	s_nop 0
	global_load_lds_dwordx4 v[8:9], off
	s_mov_b32 m0, s31
	v_lshl_add_u64 v[8:9], v[6:7], 0, s[50:51]
	s_add_i32 s30, s29, 0xe000
	s_mov_b32 s31, m0
	s_mov_b32 m0, s30
	s_nop 0
	global_load_lds_dwordx4 v[8:9], off
	s_mov_b32 m0, s31
	s_add_i32 s30, s29, 0x10000
	v_lshl_add_u64 v[8:9], v[2:3], 0, s[52:53]
	s_mov_b32 s31, m0
	s_mov_b32 m0, s30
	s_nop 0
	global_load_lds_dwordx4 v[8:9], off
	s_mov_b32 m0, s31
	v_lshl_add_u64 v[2:3], v[2:3], 0, s[54:55]
	s_add_i32 s30, s29, 0x12000
	s_mov_b32 s31, m0
	s_mov_b32 m0, s30
	s_nop 0
	global_load_lds_dwordx4 v[2:3], off
	s_mov_b32 m0, s31
	v_lshl_add_u64 v[2:3], v[6:7], 0, s[56:57]
	s_add_i32 s30, s29, 0x14000
	v_lshl_add_u64 v[2:3], v[6:7], 0, s[58:59]
	s_add_i32 s30, s29, 0x16000
	ds_read_b32 v2, v197 offset:14336
	ds_read_b32 v3, v197 offset:16124
	s_cmpk_lt_u32 s33, 0x100
	s_cselect_b64 s[62:63], -1, 0
	s_and_b64 s[30:31], s[62:63], exec
	s_cselect_b32 s30, 0, 0x2000
	v_or_b32_e32 v162, s30, v177
	s_waitcnt lgkmcnt(1)
	v_readfirstlane_b32 s30, v2
	s_waitcnt lgkmcnt(0)
	v_readfirstlane_b32 s31, v3
	v_lshlrev_b64 v[2:3], 7, v[0:1]
	v_mad_i64_i32 v[6:7], s[64:65], s76, v198, v[2:3]
	v_mad_i64_i32 v[2:3], s[64:65], s76, v199, v[2:3]
	v_or_b32_e32 v6, v6, v4
	v_or_b32_e32 v2, v2, v4
	v_lshlrev_b32_e32 v0, 2, v10
	v_mov_b32_e32 v14, v1
	v_mov_b32_e32 v15, v1
	v_lshl_add_u64 v[172:173], s[20:21], 0, v[6:7]
	v_lshl_add_u64 v[174:175], s[16:17], 0, v[2:3]
	v_sub_u32_e32 v171, v195, v0
	v_mov_b32_e32 v0, v1
	v_mov_b32_e32 v2, v1
	v_mov_b32_e32 v3, v1
	v_mov_b32_e32 v4, v1
	v_mov_b32_e32 v6, v1
	v_mov_b32_e32 v7, v1
	v_mov_b32_e32 v8, v1
	v_mov_b32_e32 v9, v1
	v_mov_b32_e32 v10, v1
	v_mov_b32_e32 v11, v1
	v_mov_b32_e32 v12, v1
	v_mov_b32_e32 v13, v1
	v_mov_b64_e32 v[64:65], v[14:15]
	v_mov_b64_e32 v[48:49], v[14:15]
	v_mov_b64_e32 v[32:33], v[14:15]
	v_mov_b64_e32 v[62:63], v[12:13]
	v_mov_b64_e32 v[60:61], v[10:11]
	v_mov_b64_e32 v[58:59], v[8:9]
	v_mov_b64_e32 v[56:57], v[6:7]
	v_mov_b64_e32 v[54:55], v[4:5]
	v_mov_b64_e32 v[52:53], v[2:3]
	v_mov_b64_e32 v[50:51], v[0:1]
	v_mov_b64_e32 v[46:47], v[12:13]
	v_mov_b64_e32 v[44:45], v[10:11]
	v_mov_b64_e32 v[42:43], v[8:9]
	v_mov_b64_e32 v[40:41], v[6:7]
	v_mov_b64_e32 v[38:39], v[4:5]
	v_mov_b64_e32 v[36:37], v[2:3]
	v_mov_b64_e32 v[34:35], v[0:1]
	v_mov_b64_e32 v[30:31], v[12:13]
	v_mov_b64_e32 v[28:29], v[10:11]
	v_mov_b64_e32 v[26:27], v[8:9]
	v_mov_b64_e32 v[24:25], v[6:7]
	v_mov_b64_e32 v[22:23], v[4:5]
	v_mov_b64_e32 v[20:21], v[2:3]
	v_mov_b64_e32 v[18:19], v[0:1]
	v_mov_b64_e32 v[16:17], v[14:15]
	s_add_i32 s33, s28, 0x9f
	s_add_i32 s67, s28, 0xffffff41
	s_mov_b32 s76, 0
	s_mov_b32 s77, 0
	s_mov_b32 s78, 0x10000
	v_mov_b64_e32 v[14:15], v[12:13]
	v_mov_b64_e32 v[12:13], v[10:11]
	v_mov_b64_e32 v[10:11], v[8:9]
	v_mov_b64_e32 v[8:9], v[6:7]
	v_mov_b64_e32 v[6:7], v[4:5]
	v_mov_b64_e32 v[4:5], v[2:3]
	v_mov_b64_e32 v[2:3], v[0:1]
	v_mov_b32_e32 v0, 0
	v_mov_b32_e32 v201, 0
	v_mov_b32_e32 v202, 0
	s_mov_b32 s79, 0
	v_mov_b32_e32 v66, 0
	v_mov_b32_e32 v67, v1
	v_mov_b32_e32 v68, v1
	v_mov_b32_e32 v69, v1
	v_mov_b32_e32 v70, v1
	v_mov_b32_e32 v71, v1
	v_mov_b32_e32 v72, v1
	v_mov_b32_e32 v73, v1
	v_mov_b32_e32 v74, v1
	v_mov_b32_e32 v75, v1
	v_mov_b32_e32 v76, v1
	v_mov_b32_e32 v77, v1
	v_mov_b32_e32 v78, v1
	v_mov_b32_e32 v79, v1
	v_mov_b32_e32 v80, v1
	v_mov_b32_e32 v81, v1
	s_mov_b32 s98, 0xfffec000
	s_mov_b32 s99, -1
	v_lshl_add_u64 v[172:173], v[172:173], 0, s[98:99]
	s_mov_b32 s98, 0xfffcc000
	s_waitcnt vmcnt(10)
	v_mbcnt_lo_u32_b32 v82, -1, 0
	v_mbcnt_hi_u32_b32 v82, -1, v82
	v_and_b32_e32 v83, 15, v82
	v_lshrrev_b32_e32 v84, 2, v83
	v_and_b32_e32 v85, 3, v83
	v_lshrrev_b32_e32 v86, 1, v84
	v_xor_b32_e32 v87, v86, v84
	v_and_b32_e32 v87, 1, v87
	v_xor_b32_e32 v87, 1, v87
	v_lshlrev_b32_e32 v87, 1, v87
	v_lshl_add_u32 v87, v86, 3, v87
	v_and_b32_e32 v88, 1, v85
	v_add_u32_e32 v87, v87, v88
	v_lshrrev_b32_e32 v88, 1, v85
	v_lshl_add_u32 v87, v88, 2, v87
	v_lshrrev_b32_e32 v88, 1, v87
	v_lshrrev_b32_e32 v89, 4, v82
	v_lshrrev_b32_e32 v90, 1, v89
	v_and_b32_e32 v89, 1, v89
	v_lshl_or_b32 v89, v89, 1, v90
	v_xor_b32_e32 v88, v88, v89
	v_lshlrev_b32_e32 v88, 4, v88
	v_lshl_add_u32 v179, v87, 7, v88
	v_xor_b32_e32 v181, 64, v179
	s_branch .LSPs_top

; #define ALAS __attribute__((address_space(3)))
; #define MX3(a, b, c) __builtin_fmaxf(__builtin_fmaxf((a), (b)), (c))
; template <bool WIN> ...
;     ...
;             const ALAS unsigned char* sb = lds + (tr & (NSTG - 1)) * STAGE;
;             {
;                 bf16x8 ka[8];
; #pragma unroll
;                 for (int ds = 0; ds < 4; ++ds) { ka[2 * ds] = *(const ALAS bf16x8*)(sb + kx[ds]); ka[2 * ds + 1] = *(const ALAS bf16x8*)(sb + kx[ds] + 4096); }
;                 __builtin_amdgcn_sched_barrier(0);
;                 s0 = __builtin_amdgcn_mfma_f32_32x32x16_bf16(ka[0], qf(0), cvec, 0, 0, 0);
;                 s1 = __builtin_amdgcn_mfma_f32_32x32x16_bf16(ka[1], qf(0), cvec, 0, 0, 0);
; #pragma unroll
;                 for (int ds = 1; ds < 4; ++ds) {
;                     s0 = __builtin_amdgcn_mfma_f32_32x32x16_bf16(ka[2 * ds], qf(ds), s0, 0, 0, 0);
;                     s1 = __builtin_amdgcn_mfma_f32_32x32x16_bf16(ka[2 * ds + 1], qf(ds), s1, 0, 0, 0);
;                 }
;             }
;             bf16x8 va[2 * NDB], vc[2 * NDB];
; #pragma unroll
;             for (int kk = 0; kk < 2; ++kk)
; #pragma unroll
;                 for (int db = 0; db < NDB; ++db) va[kk * NDB + db] = *(const ALAS bf16x8*)(sb + vx[kk] + db * 4096);
;             __builtin_amdgcn_sched_barrier(0);
;             if (near) {
;                 const ALAS float* lb = lut + (k0 + 8 * hi - qabs + LUTC);
; #pragma unroll
;                 for (int r = 0; r < 16; ++r) { s0[r] += lb[16 * (r >> 3) + (r & 7)]; s1[r] += lb[32 + 16 * (r >> 3) + (r & 7)];
;                     if ((r & 7) == 7) __builtin_amdgcn_sched_barrier(0); }
;             }
;     ...
;             float mxa = MX3(s0[0], s0[1], s1[0]), mxb = MX3(s0[2], s0[3], s1[1]);
;             mxa = MX3(mxa, s1[2], s1[3]);
; #pragma unroll
;             for (int r = 4; r < 16; r += 4) { mxa = MX3(mxa, s0[r], s0[r + 1]); mxb = MX3(mxb, s0[r + 2], s0[r + 3]); mxa = MX3(mxa, s1[r], s1[r + 1]); mxb = MX3(mxb, s1[r + 2], s1[r + 3]); }
;     ...
;             float mx = fmaxf(mxa, mxb);
;             if (__any(mx > THR)) {
.LSPs_qk:
	s_add_i32 s80, s78, 0xffff0000
	s_and_b32 s80, s80, 0x18000
	s_add_i32 s99, s78, 0xfffe8000
	s_and_b32 s99, s99, 0x18000
	v_add3_u32 v203, s80, v178, v162
	ds_read_b128 v[130:133], v203
	ds_read_b128 v[134:137], v203 offset:4096
	v_add3_u32 v203, s80, v180, v162
	ds_read_b128 v[138:141], v203
	ds_read_b128 v[142:145], v203 offset:4096
	v_add3_u32 v203, s80, v182, v162
	ds_read_b128 v[146:149], v203
	ds_read_b128 v[150:153], v203 offset:4096
	v_add3_u32 v203, s80, v184, v162
	ds_read_b128 v[158:161], v203
	ds_read_b128 v[204:207], v203 offset:4096
	s_waitcnt lgkmcnt(0)
	v_mfma_f32_32x32x16_bf16 v[98:113], v[130:133], v[126:129], v[66:81]
	v_mfma_f32_32x32x16_bf16 v[82:97], v[134:137], v[126:129], v[66:81]
	v_mfma_f32_32x32x16_bf16 v[98:113], v[138:141], v[122:125], v[98:113]
	v_mfma_f32_32x32x16_bf16 v[82:97], v[142:145], v[122:125], v[82:97]
	v_mfma_f32_32x32x16_bf16 v[98:113], v[146:149], v[118:121], v[98:113]
	v_mfma_f32_32x32x16_bf16 v[82:97], v[150:153], v[118:121], v[82:97]
	v_mfma_f32_32x32x16_bf16 v[98:113], v[158:161], v[114:117], v[98:113]
	v_mfma_f32_32x32x16_bf16 v[82:97], v[204:207], v[114:117], v[82:97]
	v_add_u32_e32 v236, s99, v179
	ds_read_b128 v[146:149], v236 offset:16384
	ds_read_b128 v[150:153], v236 offset:18432
	ds_read_b128 v[154:157], v236 offset:20480
	ds_read_b128 v[158:161], v236 offset:22528
	v_add_u32_e32 v237, s99, v179
	ds_read_b128 v[130:133], v237 offset:24576
	ds_read_b128 v[134:137], v237 offset:26624
	ds_read_b128 v[138:141], v237 offset:28672
	ds_read_b128 v[142:145], v237 offset:30720
	s_nop 1
	s_andn2_b64 vcc, exec, s[64:65]
	s_cbranch_vccnz .LSPs_max
	v_add_u32_e32 v203, s77, v171
	v_add_u32_e32 v204, 0x23b80, v203
	v_add_u32_e32 v206, 0x23c00, v203
	v_add_u32_e32 v210, 0x23c08, v203
	v_add_u32_e32 v208, 0x23b88, v203
	v_add_u32_e32 v218, 0x23c10, v203
	v_add_u32_e32 v212, 0x23b90, v203
	v_add_u32_e32 v216, 0x23c18, v203
	v_add_u32_e32 v214, 0x23b98, v203
	ds_read2_b32 v[204:205], v204 offset1:1
	ds_read2_b32 v[206:207], v206 offset1:1
	ds_read2_b32 v[208:209], v208 offset1:1
	ds_read2_b32 v[210:211], v210 offset1:1
	ds_read2_b32 v[212:213], v212 offset1:1
	ds_read2_b32 v[214:215], v214 offset1:1
	ds_read2_b32 v[216:217], v216 offset1:1
	ds_read2_b32 v[218:219], v218 offset1:1
	v_add_u32_e32 v220, 0x23bc0, v203
	v_add_u32_e32 v222, 0x23c40, v203
	v_add_u32_e32 v226, 0x23c48, v203
	v_add_u32_e32 v224, 0x23bc8, v203
	v_add_u32_e32 v228, 0x23bd0, v203
	v_add_u32_e32 v234, 0x23c58, v203
	ds_read2_b32 v[220:221], v220 offset1:1
	ds_read2_b32 v[222:223], v222 offset1:1
	ds_read2_b32 v[224:225], v224 offset1:1
	ds_read2_b32 v[226:227], v226 offset1:1
	v_add_u32_e32 v231, 0x23c50, v203
	v_add_u32_e32 v203, 0x23bd8, v203
	ds_read2_b32 v[228:229], v228 offset1:1
	ds_read2_b32 v[232:233], v203 offset1:1
	ds_read2_b32 v[234:235], v234 offset1:1
	ds_read2_b32 v[236:237], v231 offset1:1
	s_waitcnt lgkmcnt(10)
	v_pk_add_f32 v[104:105], v[104:105], v[214:215]
	v_pk_add_f32 v[102:103], v[102:103], v[212:213]
	v_pk_add_f32 v[100:101], v[100:101], v[208:209]
	s_waitcnt lgkmcnt(2)
	v_pk_add_f32 v[112:113], v[112:113], v[232:233]
	v_pk_add_f32 v[110:111], v[110:111], v[228:229]
	v_pk_add_f32 v[108:109], v[108:109], v[224:225]
	v_pk_add_f32 v[106:107], v[106:107], v[220:221]
	v_pk_add_f32 v[98:99], v[98:99], v[204:205]
	v_pk_add_f32 v[88:89], v[88:89], v[216:217]
	v_pk_add_f32 v[86:87], v[86:87], v[218:219]
	v_pk_add_f32 v[84:85], v[84:85], v[210:211]
	s_waitcnt lgkmcnt(1)
	v_pk_add_f32 v[96:97], v[96:97], v[234:235]
	s_waitcnt lgkmcnt(0)
	v_pk_add_f32 v[94:95], v[94:95], v[236:237]
	v_pk_add_f32 v[92:93], v[92:93], v[226:227]
	v_pk_add_f32 v[90:91], v[90:91], v[222:223]
	v_pk_add_f32 v[82:83], v[82:83], v[206:207]
.LSPs_max:
	s_nop 0
	v_max_f32_e32 v203, v99, v99
	v_max_f32_e32 v204, v98, v98
	v_max_f32_e32 v203, v204, v203
	s_nop 5
	v_max3_f32 v204, v100, v101, v83
	v_max3_f32 v203, v203, v82, v84
	v_max3_f32 v203, v203, v85, v102
	v_max3_f32 v204, v204, v104, v105
	v_max3_f32 v203, v203, v103, v86
	v_max3_f32 v204, v204, v88, v89
	v_max3_f32 v203, v203, v87, v106
	v_max3_f32 v204, v204, v108, v109
	v_max3_f32 v203, v203, v107, v90
	v_max3_f32 v204, v204, v92, v93
	v_max3_f32 v203, v203, v91, v110
	v_max3_f32 v204, v204, v112, v113
	v_max3_f32 v203, v203, v111, v94
	v_max3_f32 v204, v204, v96, v97
	v_max3_f32 v203, v203, v95, v204
	v_cmp_lt_f32_e32 vcc, s24, v203
	s_cbranch_vccz .LSPs_pv
	s_cmp_eq_u32 s79, 0
	s_cbranch_scc1 .LSPs_rnopv
; template <bool WIN> ...
;     ...
;                 mx = fmaxf(mx, __shfl_xor(mx, 32));
;                 const float dl = fmaxf(mx, 0.f);
;                 m_ref += dl;
;                 const float f = __builtin_amdgcn_exp2f(-dl);
;                 l_run *= f;
; #pragma unroll
;                 for (int db = 0; db < NDB; ++db)
; #pragma unroll
;                     for (int r = 0; r < 16; ++r) o[db][r] *= f;
; #pragma unroll
;                 for (int r = 0; r < 16; ++r) { s0[r] -= dl; s1[r] -= dl; cvec[r] = cbase - m_ref; }
;     ...
;             for (int db = 0; db < NDB; ++db) o[db] = __builtin_amdgcn_mfma_f32_32x32x16_bf16(va[db], p0.b, o[db], 0, 0, 0);
;             AT_EXP(s0, 8, p1);
;             __builtin_amdgcn_sched_barrier(0);
; #pragma unroll
;             for (int db = 0; db < NDB; ++db) o[db] = __builtin_amdgcn_mfma_f32_32x32x16_bf16(va[NDB + db], p1.b, o[db], 0, 0, 0);
;             AT_EXP(s1, 0, p2);
;             __builtin_amdgcn_sched_barrier(0);
; #pragma unroll
;             for (int db = 0; db < NDB; ++db) o[db] = __builtin_amdgcn_mfma_f32_32x32x16_bf16(vc[db], p2.b, o[db], 0, 0, 0);
;             AT_EXP(s1, 8, p3);
;             __builtin_amdgcn_sched_barrier(0);
; #pragma unroll
;             for (int db = 0; db < NDB; ++db) o[db] = __builtin_amdgcn_mfma_f32_32x32x16_bf16(vc[NDB + db], p3.b, o[db], 0, 0, 0);
	s_waitcnt lgkmcnt(0)
	v_add_u32_e32 v236, s99, v179
	ds_read_b128 v[146:149], v236 offset:16384
	ds_read_b128 v[150:153], v236 offset:18432
	ds_read_b128 v[154:157], v236 offset:20480
	ds_read_b128 v[158:161], v236 offset:22528
	v_add_u32_e32 v237, s99, v179
	ds_read_b128 v[130:133], v237 offset:24576
	ds_read_b128 v[134:137], v237 offset:26624
	ds_read_b128 v[138:141], v237 offset:28672
	ds_read_b128 v[142:145], v237 offset:30720
	s_waitcnt lgkmcnt(4)
	v_mfma_f32_16x16x32_bf16 v[2:5], v[146:149], v[238:241], v[2:5]
	v_mfma_f32_16x16x32_bf16 v[6:9], v[146:149], v[242:245], v[6:9]
	v_mfma_f32_16x16x32_bf16 v[10:13], v[150:153], v[238:241], v[10:13]
	v_mfma_f32_16x16x32_bf16 v[14:17], v[150:153], v[242:245], v[14:17]
	v_mfma_f32_16x16x32_bf16 v[18:21], v[154:157], v[238:241], v[18:21]
	v_mfma_f32_16x16x32_bf16 v[22:25], v[154:157], v[242:245], v[22:25]
	v_mfma_f32_16x16x32_bf16 v[26:29], v[158:161], v[238:241], v[26:29]
	v_mfma_f32_16x16x32_bf16 v[30:33], v[158:161], v[242:245], v[30:33]
	v_add_u32_e32 v236, s99, v181
	ds_read_b128 v[146:149], v236 offset:16384
	ds_read_b128 v[150:153], v236 offset:18432
	ds_read_b128 v[154:157], v236 offset:20480
	ds_read_b128 v[158:161], v236 offset:22528
	s_waitcnt lgkmcnt(4)
	v_mfma_f32_16x16x32_bf16 v[34:37], v[130:133], v[238:241], v[34:37]
	v_mfma_f32_16x16x32_bf16 v[38:41], v[130:133], v[242:245], v[38:41]
	v_mfma_f32_16x16x32_bf16 v[42:45], v[134:137], v[238:241], v[42:45]
	v_mfma_f32_16x16x32_bf16 v[46:49], v[134:137], v[242:245], v[46:49]
	v_mfma_f32_16x16x32_bf16 v[50:53], v[138:141], v[238:241], v[50:53]
	v_mfma_f32_16x16x32_bf16 v[54:57], v[138:141], v[242:245], v[54:57]
	v_mfma_f32_16x16x32_bf16 v[58:61], v[142:145], v[238:241], v[58:61]
	v_mfma_f32_16x16x32_bf16 v[62:65], v[142:145], v[242:245], v[62:65]
	v_add_u32_e32 v237, s99, v181
	ds_read_b128 v[130:133], v237 offset:24576
	ds_read_b128 v[134:137], v237 offset:26624
	ds_read_b128 v[138:141], v237 offset:28672
	ds_read_b128 v[142:145], v237 offset:30720
	s_waitcnt lgkmcnt(4)
	v_mfma_f32_16x16x32_bf16 v[2:5], v[146:149], v[246:249], v[2:5]
	v_mfma_f32_16x16x32_bf16 v[6:9], v[146:149], v[250:253], v[6:9]
	v_mfma_f32_16x16x32_bf16 v[10:13], v[150:153], v[246:249], v[10:13]
	v_mfma_f32_16x16x32_bf16 v[14:17], v[150:153], v[250:253], v[14:17]
	v_mfma_f32_16x16x32_bf16 v[18:21], v[154:157], v[246:249], v[18:21]
	v_mfma_f32_16x16x32_bf16 v[22:25], v[154:157], v[250:253], v[22:25]
	v_mfma_f32_16x16x32_bf16 v[26:29], v[158:161], v[246:249], v[26:29]
	v_mfma_f32_16x16x32_bf16 v[30:33], v[158:161], v[250:253], v[30:33]
	s_waitcnt lgkmcnt(0)
	v_mfma_f32_16x16x32_bf16 v[34:37], v[130:133], v[246:249], v[34:37]
	v_mfma_f32_16x16x32_bf16 v[38:41], v[130:133], v[250:253], v[38:41]
	v_mfma_f32_16x16x32_bf16 v[42:45], v[134:137], v[246:249], v[42:45]
	v_mfma_f32_16x16x32_bf16 v[46:49], v[134:137], v[250:253], v[46:49]
	v_mfma_f32_16x16x32_bf16 v[50:53], v[138:141], v[246:249], v[50:53]
	v_mfma_f32_16x16x32_bf16 v[54:57], v[138:141], v[250:253], v[54:57]
	v_mfma_f32_16x16x32_bf16 v[58:61], v[142:145], v[246:249], v[58:61]
	v_mfma_f32_16x16x32_bf16 v[62:65], v[142:145], v[250:253], v[62:65]
	s_nop 7
	s_nop 7
.LSPs_rnopv:
	ds_bpermute_b32 v66, v176, v203
	s_waitcnt lgkmcnt(0)
	v_max3_f32 v68, v203, v66, 0
	v_exp_f32_e64 v70, -v68
	v_add_f32_e32 v201, v201, v68
	v_sub_f32_e32 v66, v202, v201
	v_pk_add_f32 v[98:99], v[98:99], v[68:69] op_sel_hi:[1,0] neg_lo:[0,1] neg_hi:[0,1]
	v_mov_b32_e32 v72, v70
	v_mov_b32_e32 v74, v70
	s_nop 1
	v_permlane16_swap_b32_e32 v72, v74
	s_nop 1
	v_pk_mul_f32 v[64:65], v[64:65], v[74:75] op_sel_hi:[1,0]
	v_pk_mul_f32 v[62:63], v[62:63], v[74:75] op_sel_hi:[1,0]
	v_pk_mul_f32 v[60:61], v[60:61], v[72:73] op_sel_hi:[1,0]
	v_pk_mul_f32 v[58:59], v[58:59], v[72:73] op_sel_hi:[1,0]
	v_pk_mul_f32 v[56:57], v[56:57], v[74:75] op_sel_hi:[1,0]
	v_pk_mul_f32 v[54:55], v[54:55], v[74:75] op_sel_hi:[1,0]
	v_pk_mul_f32 v[52:53], v[52:53], v[72:73] op_sel_hi:[1,0]
	v_pk_mul_f32 v[50:51], v[50:51], v[72:73] op_sel_hi:[1,0]
	v_pk_mul_f32 v[48:49], v[48:49], v[74:75] op_sel_hi:[1,0]
	v_pk_mul_f32 v[46:47], v[46:47], v[74:75] op_sel_hi:[1,0]
	v_pk_mul_f32 v[44:45], v[44:45], v[72:73] op_sel_hi:[1,0]
	v_pk_mul_f32 v[42:43], v[42:43], v[72:73] op_sel_hi:[1,0]
	v_pk_mul_f32 v[40:41], v[40:41], v[74:75] op_sel_hi:[1,0]
	v_pk_mul_f32 v[38:39], v[38:39], v[74:75] op_sel_hi:[1,0]
	v_pk_mul_f32 v[36:37], v[36:37], v[72:73] op_sel_hi:[1,0]
	v_pk_mul_f32 v[34:35], v[34:35], v[72:73] op_sel_hi:[1,0]
	v_pk_mul_f32 v[32:33], v[32:33], v[74:75] op_sel_hi:[1,0]
	v_pk_mul_f32 v[30:31], v[30:31], v[74:75] op_sel_hi:[1,0]
	v_pk_mul_f32 v[28:29], v[28:29], v[72:73] op_sel_hi:[1,0]
	v_pk_mul_f32 v[26:27], v[26:27], v[72:73] op_sel_hi:[1,0]
	v_pk_mul_f32 v[24:25], v[24:25], v[74:75] op_sel_hi:[1,0]
	v_pk_mul_f32 v[22:23], v[22:23], v[74:75] op_sel_hi:[1,0]
	v_pk_mul_f32 v[20:21], v[20:21], v[72:73] op_sel_hi:[1,0]
	v_pk_mul_f32 v[18:19], v[18:19], v[72:73] op_sel_hi:[1,0]
	v_pk_mul_f32 v[16:17], v[16:17], v[74:75] op_sel_hi:[1,0]
	v_pk_mul_f32 v[14:15], v[14:15], v[74:75] op_sel_hi:[1,0]
	v_pk_mul_f32 v[12:13], v[12:13], v[72:73] op_sel_hi:[1,0]
	v_pk_mul_f32 v[10:11], v[10:11], v[72:73] op_sel_hi:[1,0]
	v_pk_mul_f32 v[8:9], v[8:9], v[74:75] op_sel_hi:[1,0]
	v_pk_mul_f32 v[6:7], v[6:7], v[74:75] op_sel_hi:[1,0]
	v_pk_mul_f32 v[4:5], v[4:5], v[72:73] op_sel_hi:[1,0]
	v_pk_mul_f32 v[2:3], v[2:3], v[72:73] op_sel_hi:[1,0]
	v_pk_add_f32 v[82:83], v[82:83], v[68:69] op_sel_hi:[1,0] neg_lo:[0,1] neg_hi:[0,1]
	v_pk_add_f32 v[100:101], v[100:101], v[68:69] op_sel_hi:[1,0] neg_lo:[0,1] neg_hi:[0,1]
	v_pk_add_f32 v[84:85], v[84:85], v[68:69] op_sel_hi:[1,0] neg_lo:[0,1] neg_hi:[0,1]
; #define ALAS __attribute__((address_space(3)))
; template <bool WIN> ...
;     ...
;                 for (int r = 0; r < 16; ++r) { s0[r] -= dl; s1[r] -= dl; cvec[r] = cbase - m_ref; }
;             }
;             float ls0 = 0.f, ls1 = 0.f;
;     ...
;             union PFU { u32x4 u; bf16x8 b; };
;             PFU p0, p1, p2, p3;
;             AT_EXP(s0, 0, p0);
; #pragma unroll
;             for (int kk = 0; kk < 2; ++kk)
; #pragma unroll
;                 for (int db = 0; db < NDB; ++db) vc[kk * NDB + db] = *(const ALAS bf16x8*)(sb + vx[kk + 2] + db * 4096);
;             __builtin_amdgcn_sched_barrier(0);
; #pragma unroll
;             for (int db = 0; db < NDB; ++db) o[db] = __builtin_amdgcn_mfma_f32_32x32x16_bf16(va[db], p0.b, o[db], 0, 0, 0);
;             AT_EXP(s0, 8, p1);
;             __builtin_amdgcn_sched_barrier(0);
; #pragma unroll
;             for (int db = 0; db < NDB; ++db) o[db] = __builtin_amdgcn_mfma_f32_32x32x16_bf16(va[NDB + db], p1.b, o[db], 0, 0, 0);
;             AT_EXP(s1, 0, p2);
;             __builtin_amdgcn_sched_barrier(0);
; #pragma unroll
;             for (int db = 0; db < NDB; ++db) o[db] = __builtin_amdgcn_mfma_f32_32x32x16_bf16(vc[db], p2.b, o[db], 0, 0, 0);
;             AT_EXP(s1, 8, p3);
;             __builtin_amdgcn_sched_barrier(0);
; #pragma unroll
;             for (int db = 0; db < NDB; ++db) o[db] = __builtin_amdgcn_mfma_f32_32x32x16_bf16(vc[NDB + db], p3.b, o[db], 0, 0, 0);
	v_pk_add_f32 v[102:103], v[102:103], v[68:69] op_sel_hi:[1,0] neg_lo:[0,1] neg_hi:[0,1]
	v_pk_add_f32 v[86:87], v[86:87], v[68:69] op_sel_hi:[1,0] neg_lo:[0,1] neg_hi:[0,1]
	v_pk_add_f32 v[104:105], v[104:105], v[68:69] op_sel_hi:[1,0] neg_lo:[0,1] neg_hi:[0,1]
	v_pk_add_f32 v[88:89], v[88:89], v[68:69] op_sel_hi:[1,0] neg_lo:[0,1] neg_hi:[0,1]
	v_pk_add_f32 v[106:107], v[106:107], v[68:69] op_sel_hi:[1,0] neg_lo:[0,1] neg_hi:[0,1]
	v_pk_add_f32 v[90:91], v[90:91], v[68:69] op_sel_hi:[1,0] neg_lo:[0,1] neg_hi:[0,1]
	v_pk_add_f32 v[108:109], v[108:109], v[68:69] op_sel_hi:[1,0] neg_lo:[0,1] neg_hi:[0,1]
	v_pk_add_f32 v[92:93], v[92:93], v[68:69] op_sel_hi:[1,0] neg_lo:[0,1] neg_hi:[0,1]
	v_pk_add_f32 v[110:111], v[110:111], v[68:69] op_sel_hi:[1,0] neg_lo:[0,1] neg_hi:[0,1]
	v_pk_add_f32 v[94:95], v[94:95], v[68:69] op_sel_hi:[1,0] neg_lo:[0,1] neg_hi:[0,1]
	v_pk_add_f32 v[112:113], v[112:113], v[68:69] op_sel_hi:[1,0] neg_lo:[0,1] neg_hi:[0,1]
	v_pk_add_f32 v[96:97], v[96:97], v[68:69] op_sel_hi:[1,0] neg_lo:[0,1] neg_hi:[0,1]
	v_mul_f32_e32 v0, v0, v70
	v_mov_b32_e32 v67, v66
	v_mov_b32_e32 v68, v66
	v_mov_b32_e32 v69, v66
	v_mov_b32_e32 v70, v66
	v_mov_b32_e32 v71, v66
	v_mov_b32_e32 v72, v66
	v_mov_b32_e32 v73, v66
	v_mov_b32_e32 v74, v66
	v_mov_b32_e32 v75, v66
	v_mov_b32_e32 v76, v66
	v_mov_b32_e32 v77, v66
	v_mov_b32_e32 v78, v66
	v_mov_b32_e32 v79, v66
	v_mov_b32_e32 v80, v66
	v_mov_b32_e32 v81, v66
	s_branch .LSPs_pure
.LSPs_pv:
	s_cmp_eq_u32 s79, 0
	s_cbranch_scc1 .LSPs_pure
	v_mov_b32_e32 v228, 0
	v_mov_b32_e32 v229, 0
	s_waitcnt lgkmcnt(4)
	v_mfma_f32_16x16x32_bf16 v[2:5], v[146:149], v[238:241], v[2:5]
	v_exp_f32_e32 v98, v98
	v_mfma_f32_16x16x32_bf16 v[6:9], v[146:149], v[242:245], v[6:9]
	v_exp_f32_e32 v99, v99
	v_add_f32_e32 v229, v229, v98
	v_mfma_f32_16x16x32_bf16 v[10:13], v[150:153], v[238:241], v[10:13]
	v_exp_f32_e32 v100, v100
	v_add_f32_e32 v228, v228, v99
	v_mfma_f32_16x16x32_bf16 v[14:17], v[150:153], v[242:245], v[14:17]
	v_exp_f32_e32 v101, v101
	v_add_f32_e32 v229, v229, v100
	v_mfma_f32_16x16x32_bf16 v[18:21], v[154:157], v[238:241], v[18:21]
	v_exp_f32_e32 v102, v102
	v_add_f32_e32 v228, v228, v101
	v_mfma_f32_16x16x32_bf16 v[22:25], v[154:157], v[242:245], v[22:25]
	v_exp_f32_e32 v103, v103
	v_add_f32_e32 v229, v229, v102
	v_mfma_f32_16x16x32_bf16 v[26:29], v[158:161], v[238:241], v[26:29]
	v_exp_f32_e32 v104, v104
	v_add_f32_e32 v228, v228, v103
	v_mfma_f32_16x16x32_bf16 v[30:33], v[158:161], v[242:245], v[30:33]
	v_exp_f32_e32 v105, v105
	v_add_f32_e32 v229, v229, v104
	v_add_u32_e32 v236, s99, v181
	ds_read_b128 v[146:149], v236 offset:16384
	ds_read_b128 v[150:153], v236 offset:18432
	ds_read_b128 v[154:157], v236 offset:20480
	ds_read_b128 v[158:161], v236 offset:22528
	s_waitcnt lgkmcnt(4)
	v_mfma_f32_16x16x32_bf16 v[34:37], v[130:133], v[238:241], v[34:37]
	v_exp_f32_e32 v106, v106
	v_add_f32_e32 v228, v228, v105
	v_mfma_f32_16x16x32_bf16 v[38:41], v[130:133], v[242:245], v[38:41]
	v_exp_f32_e32 v107, v107
	v_add_f32_e32 v229, v229, v106
	v_mfma_f32_16x16x32_bf16 v[42:45], v[134:137], v[238:241], v[42:45]
	v_exp_f32_e32 v108, v108
	v_add_f32_e32 v228, v228, v107
	v_mfma_f32_16x16x32_bf16 v[46:49], v[134:137], v[242:245], v[46:49]
	v_exp_f32_e32 v109, v109
	v_add_f32_e32 v229, v229, v108
	v_mfma_f32_16x16x32_bf16 v[50:53], v[138:141], v[238:241], v[50:53]
	v_exp_f32_e32 v110, v110
	v_add_f32_e32 v228, v228, v109
	v_mfma_f32_16x16x32_bf16 v[54:57], v[138:141], v[242:245], v[54:57]
	v_exp_f32_e32 v111, v111
	v_add_f32_e32 v229, v229, v110
	v_mfma_f32_16x16x32_bf16 v[58:61], v[142:145], v[238:241], v[58:61]
	v_exp_f32_e32 v112, v112
	v_add_f32_e32 v228, v228, v111
	v_mfma_f32_16x16x32_bf16 v[62:65], v[142:145], v[242:245], v[62:65]
	v_exp_f32_e32 v113, v113
	v_add_f32_e32 v229, v229, v112
	v_add_u32_e32 v237, s99, v181
	ds_read_b128 v[130:133], v237 offset:24576
	ds_read_b128 v[134:137], v237 offset:26624
	ds_read_b128 v[138:141], v237 offset:28672
	ds_read_b128 v[142:145], v237 offset:30720
	s_waitcnt lgkmcnt(4)
	v_mfma_f32_16x16x32_bf16 v[2:5], v[146:149], v[246:249], v[2:5]
	v_exp_f32_e32 v82, v82
	v_add_f32_e32 v228, v228, v113
	v_cvt_pk_bf16_f32 v238, v98, v99
	v_mfma_f32_16x16x32_bf16 v[6:9], v[146:149], v[250:253], v[6:9]
	v_exp_f32_e32 v83, v83
	v_add_f32_e32 v229, v229, v82
	v_cvt_pk_bf16_f32 v239, v100, v101
	v_mfma_f32_16x16x32_bf16 v[10:13], v[150:153], v[246:249], v[10:13]
	v_exp_f32_e32 v84, v84
	v_add_f32_e32 v228, v228, v83
	v_cvt_pk_bf16_f32 v240, v102, v103
	v_mfma_f32_16x16x32_bf16 v[14:17], v[150:153], v[250:253], v[14:17]
	v_exp_f32_e32 v85, v85
	v_add_f32_e32 v229, v229, v84
	v_cvt_pk_bf16_f32 v241, v104, v105
	v_mfma_f32_16x16x32_bf16 v[18:21], v[154:157], v[246:249], v[18:21]
	v_exp_f32_e32 v86, v86
	v_add_f32_e32 v228, v228, v85
	v_cvt_pk_bf16_f32 v242, v106, v107
	v_mfma_f32_16x16x32_bf16 v[22:25], v[154:157], v[250:253], v[22:25]
	v_exp_f32_e32 v87, v87
	v_add_f32_e32 v229, v229, v86
	v_cvt_pk_bf16_f32 v243, v108, v109
	v_mfma_f32_16x16x32_bf16 v[26:29], v[158:161], v[246:249], v[26:29]
	v_exp_f32_e32 v88, v88
	v_add_f32_e32 v228, v228, v87
	v_cvt_pk_bf16_f32 v244, v110, v111
	v_mfma_f32_16x16x32_bf16 v[30:33], v[158:161], v[250:253], v[30:33]
	v_exp_f32_e32 v89, v89
	v_add_f32_e32 v229, v229, v88
	v_cvt_pk_bf16_f32 v245, v112, v113
	s_waitcnt lgkmcnt(0)
; #define ALAS __attribute__((address_space(3)))
; template <bool WIN> ...
;     ...
;             float ls0 = 0.f, ls1 = 0.f;
;     ...
;             union PFU { u32x4 u; bf16x8 b; };
;             PFU p0, p1, p2, p3;
;             AT_EXP(s0, 0, p0);
; #pragma unroll
;             for (int kk = 0; kk < 2; ++kk)
; #pragma unroll
;                 for (int db = 0; db < NDB; ++db) vc[kk * NDB + db] = *(const ALAS bf16x8*)(sb + vx[kk + 2] + db * 4096);
;             __builtin_amdgcn_sched_barrier(0);
; #pragma unroll
;             for (int db = 0; db < NDB; ++db) o[db] = __builtin_amdgcn_mfma_f32_32x32x16_bf16(va[db], p0.b, o[db], 0, 0, 0);
;             AT_EXP(s0, 8, p1);
;             __builtin_amdgcn_sched_barrier(0);
; #pragma unroll
;             for (int db = 0; db < NDB; ++db) o[db] = __builtin_amdgcn_mfma_f32_32x32x16_bf16(va[NDB + db], p1.b, o[db], 0, 0, 0);
;             AT_EXP(s1, 0, p2);
;             __builtin_amdgcn_sched_barrier(0);
; #pragma unroll
;             for (int db = 0; db < NDB; ++db) o[db] = __builtin_amdgcn_mfma_f32_32x32x16_bf16(vc[db], p2.b, o[db], 0, 0, 0);
;             AT_EXP(s1, 8, p3);
;             __builtin_amdgcn_sched_barrier(0);
; #pragma unroll
;             for (int db = 0; db < NDB; ++db) o[db] = __builtin_amdgcn_mfma_f32_32x32x16_bf16(vc[NDB + db], p3.b, o[db], 0, 0, 0);
;             __builtin_amdgcn_sched_barrier(0);
;     ...
;             l_run += ls0 + ls1;
	v_mfma_f32_16x16x32_bf16 v[34:37], v[130:133], v[246:249], v[34:37]
	v_exp_f32_e32 v90, v90
	v_add_f32_e32 v228, v228, v89
	v_mfma_f32_16x16x32_bf16 v[38:41], v[130:133], v[250:253], v[38:41]
	v_exp_f32_e32 v91, v91
	v_add_f32_e32 v229, v229, v90
	v_mfma_f32_16x16x32_bf16 v[42:45], v[134:137], v[246:249], v[42:45]
	v_exp_f32_e32 v92, v92
	v_add_f32_e32 v228, v228, v91
	v_mfma_f32_16x16x32_bf16 v[46:49], v[134:137], v[250:253], v[46:49]
	v_exp_f32_e32 v93, v93
	v_add_f32_e32 v229, v229, v92
	v_mfma_f32_16x16x32_bf16 v[50:53], v[138:141], v[246:249], v[50:53]
	v_exp_f32_e32 v94, v94
	v_add_f32_e32 v228, v228, v93
	v_mfma_f32_16x16x32_bf16 v[54:57], v[138:141], v[250:253], v[54:57]
	v_exp_f32_e32 v95, v95
	v_add_f32_e32 v229, v229, v94
	v_mfma_f32_16x16x32_bf16 v[58:61], v[142:145], v[246:249], v[58:61]
	v_exp_f32_e32 v96, v96
	v_add_f32_e32 v228, v228, v95
	v_mfma_f32_16x16x32_bf16 v[62:65], v[142:145], v[250:253], v[62:65]
	v_exp_f32_e32 v97, v97
	v_add_f32_e32 v229, v229, v96
	v_add_f32_e32 v228, v228, v97
	v_cvt_pk_bf16_f32 v246, v82, v83
	v_cvt_pk_bf16_f32 v247, v84, v85
	v_cvt_pk_bf16_f32 v248, v86, v87
	v_cvt_pk_bf16_f32 v249, v88, v89
	v_cvt_pk_bf16_f32 v250, v90, v91
	v_cvt_pk_bf16_f32 v251, v92, v93
	v_cvt_pk_bf16_f32 v252, v94, v95
	v_cvt_pk_bf16_f32 v253, v96, v97
	s_nop 1
	v_permlane16_swap_b32_e32 v238, v242
	v_permlane16_swap_b32_e32 v239, v243
	v_permlane16_swap_b32_e32 v240, v244
	v_permlane16_swap_b32_e32 v241, v245
	v_permlane16_swap_b32_e32 v246, v250
	v_permlane16_swap_b32_e32 v247, v251
	v_permlane16_swap_b32_e32 v248, v252
	v_permlane16_swap_b32_e32 v249, v253
	v_add_f32_e32 v228, v228, v229
	s_add_i32 s79, s79, 1
	s_add_i32 s78, s78, 0x8000
	s_addk_i32 s77, 0x100
	s_add_i32 s76, s76, 64
	v_add_f32_e32 v0, v0, v228
	v_lshl_add_u64 v[172:173], v[172:173], 0, s[48:49]
	s_cmpk_eq_i32 s77, 0x2000
	v_lshl_add_u64 v[174:175], v[174:175], 0, s[60:61]
	s_cbranch_scc0 .LSPs_top
	s_branch .LSPs_exit
.LSPs_pure:
	v_exp_f32_e32 v98, v98
	v_exp_f32_e32 v99, v99
	v_exp_f32_e32 v100, v100
	v_exp_f32_e32 v101, v101
	v_exp_f32_e32 v102, v102
	v_exp_f32_e32 v103, v103
	v_exp_f32_e32 v104, v104
	v_exp_f32_e32 v105, v105
	v_cvt_pk_bf16_f32 v238, v98, v99
	v_cvt_pk_bf16_f32 v239, v100, v101
	v_cvt_pk_bf16_f32 v240, v102, v103
	v_cvt_pk_bf16_f32 v241, v104, v105
	v_mov_b32_e32 v228, v98
	v_mov_b32_e32 v229, v102
	v_add_f32_e32 v228, v228, v99
	v_add_f32_e32 v229, v229, v103
	v_add_f32_e32 v228, v228, v100
	v_add_f32_e32 v229, v229, v104
	v_add_f32_e32 v228, v228, v101
	v_add_f32_e32 v229, v229, v105
	v_exp_f32_e32 v106, v106
	v_exp_f32_e32 v107, v107
	v_exp_f32_e32 v108, v108
	v_exp_f32_e32 v109, v109
	v_exp_f32_e32 v110, v110
	v_exp_f32_e32 v111, v111
	v_exp_f32_e32 v112, v112
	v_exp_f32_e32 v113, v113
	v_cvt_pk_bf16_f32 v242, v106, v107
	v_cvt_pk_bf16_f32 v243, v108, v109
	v_cvt_pk_bf16_f32 v244, v110, v111
	v_cvt_pk_bf16_f32 v245, v112, v113
	v_add_f32_e32 v228, v228, v106
	v_add_f32_e32 v229, v229, v110
	v_add_f32_e32 v228, v228, v107
	v_add_f32_e32 v229, v229, v111
	v_add_f32_e32 v228, v228, v108
	v_add_f32_e32 v229, v229, v112
	v_add_f32_e32 v228, v228, v109
	v_add_f32_e32 v229, v229, v113
	v_exp_f32_e32 v82, v82
	v_exp_f32_e32 v83, v83
	v_exp_f32_e32 v84, v84
	v_exp_f32_e32 v85, v85
	v_exp_f32_e32 v86, v86
	v_exp_f32_e32 v87, v87
	v_exp_f32_e32 v88, v88
	v_exp_f32_e32 v89, v89
	v_cvt_pk_bf16_f32 v246, v82, v83
	v_cvt_pk_bf16_f32 v247, v84, v85
	v_cvt_pk_bf16_f32 v248, v86, v87
	v_cvt_pk_bf16_f32 v249, v88, v89
	v_add_f32_e32 v228, v228, v82
	v_add_f32_e32 v229, v229, v86
	v_add_f32_e32 v228, v228, v83
	v_add_f32_e32 v229, v229, v87
	v_add_f32_e32 v228, v228, v84
	v_add_f32_e32 v229, v229, v88
	v_add_f32_e32 v228, v228, v85
	v_add_f32_e32 v229, v229, v89
	v_exp_f32_e32 v90, v90
	v_exp_f32_e32 v91, v91
	v_exp_f32_e32 v92, v92
	v_exp_f32_e32 v93, v93
	v_exp_f32_e32 v94, v94
	v_exp_f32_e32 v95, v95
	v_exp_f32_e32 v96, v96
	v_exp_f32_e32 v97, v97
	v_cvt_pk_bf16_f32 v250, v90, v91
	v_cvt_pk_bf16_f32 v251, v92, v93
	v_cvt_pk_bf16_f32 v252, v94, v95
	v_cvt_pk_bf16_f32 v253, v96, v97
	v_add_f32_e32 v228, v228, v90
	v_add_f32_e32 v229, v229, v94
	v_add_f32_e32 v228, v228, v91
	v_add_f32_e32 v229, v229, v95
	v_add_f32_e32 v228, v228, v92
	v_add_f32_e32 v229, v229, v96
	v_add_f32_e32 v228, v228, v93
	v_add_f32_e32 v229, v229, v97
	s_nop 1
	v_permlane16_swap_b32_e32 v238, v242
	v_permlane16_swap_b32_e32 v239, v243
	v_permlane16_swap_b32_e32 v240, v244
	v_permlane16_swap_b32_e32 v241, v245
	v_permlane16_swap_b32_e32 v246, v250
	v_permlane16_swap_b32_e32 v247, v251
	v_permlane16_swap_b32_e32 v248, v252
	v_permlane16_swap_b32_e32 v249, v253
	v_add_f32_e32 v228, v228, v229
	s_add_i32 s79, s79, 1
	s_add_i32 s78, s78, 0x8000
	s_addk_i32 s77, 0x100
	s_add_i32 s76, s76, 64
	v_add_f32_e32 v0, v0, v228
	v_lshl_add_u64 v[172:173], v[172:173], 0, s[48:49]
	s_cmpk_eq_i32 s77, 0x2000
	v_lshl_add_u64 v[174:175], v[174:175], 0, s[60:61]
	s_cbranch_scc0 .LSPs_top
	s_branch .LSPs_exit
; #define ALAS __attribute__((address_space(3)))
; template <bool WIN> ...
;     ...
;             for (int kk = 0; kk < 2; ++kk)
; #pragma unroll
;                 for (int db = 0; db < NDB; ++db) vc[kk * NDB + db] = *(const ALAS bf16x8*)(sb + vx[kk + 2] + db * 4096);
;             __builtin_amdgcn_sched_barrier(0);
; #pragma unroll
;             for (int db = 0; db < NDB; ++db) o[db] = __builtin_amdgcn_mfma_f32_32x32x16_bf16(va[db], p0.b, o[db], 0, 0, 0);
;             AT_EXP(s0, 8, p1);
;             __builtin_amdgcn_sched_barrier(0);
; #pragma unroll
;             for (int db = 0; db < NDB; ++db) o[db] = __builtin_amdgcn_mfma_f32_32x32x16_bf16(va[NDB + db], p1.b, o[db], 0, 0, 0);
;             AT_EXP(s1, 0, p2);
;             __builtin_amdgcn_sched_barrier(0);
; #pragma unroll
;             for (int db = 0; db < NDB; ++db) o[db] = __builtin_amdgcn_mfma_f32_32x32x16_bf16(vc[db], p2.b, o[db], 0, 0, 0);
;             AT_EXP(s1, 8, p3);
;             __builtin_amdgcn_sched_barrier(0);
; #pragma unroll
;             for (int db = 0; db < NDB; ++db) o[db] = __builtin_amdgcn_mfma_f32_32x32x16_bf16(vc[NDB + db], p3.b, o[db], 0, 0, 0);
.LSPs_exit:
	s_add_i32 s99, s78, 0xfffe8000
	s_and_b32 s99, s99, 0x18000
	v_add_u32_e32 v236, s99, v179
	ds_read_b128 v[146:149], v236 offset:16384
	ds_read_b128 v[150:153], v236 offset:18432
	ds_read_b128 v[154:157], v236 offset:20480
	ds_read_b128 v[158:161], v236 offset:22528
	v_add_u32_e32 v237, s99, v179
	ds_read_b128 v[130:133], v237 offset:24576
	ds_read_b128 v[134:137], v237 offset:26624
	ds_read_b128 v[138:141], v237 offset:28672
	ds_read_b128 v[142:145], v237 offset:30720
	s_waitcnt lgkmcnt(4)
	v_mfma_f32_16x16x32_bf16 v[2:5], v[146:149], v[238:241], v[2:5]
	v_mfma_f32_16x16x32_bf16 v[6:9], v[146:149], v[242:245], v[6:9]
	v_mfma_f32_16x16x32_bf16 v[10:13], v[150:153], v[238:241], v[10:13]
	v_mfma_f32_16x16x32_bf16 v[14:17], v[150:153], v[242:245], v[14:17]
	v_mfma_f32_16x16x32_bf16 v[18:21], v[154:157], v[238:241], v[18:21]
	v_mfma_f32_16x16x32_bf16 v[22:25], v[154:157], v[242:245], v[22:25]
	v_mfma_f32_16x16x32_bf16 v[26:29], v[158:161], v[238:241], v[26:29]
	v_mfma_f32_16x16x32_bf16 v[30:33], v[158:161], v[242:245], v[30:33]
	v_add_u32_e32 v236, s99, v181
	ds_read_b128 v[146:149], v236 offset:16384
	ds_read_b128 v[150:153], v236 offset:18432
	ds_read_b128 v[154:157], v236 offset:20480
	ds_read_b128 v[158:161], v236 offset:22528
	s_waitcnt lgkmcnt(4)
	v_mfma_f32_16x16x32_bf16 v[34:37], v[130:133], v[238:241], v[34:37]
	v_mfma_f32_16x16x32_bf16 v[38:41], v[130:133], v[242:245], v[38:41]
	v_mfma_f32_16x16x32_bf16 v[42:45], v[134:137], v[238:241], v[42:45]
	v_mfma_f32_16x16x32_bf16 v[46:49], v[134:137], v[242:245], v[46:49]
	v_mfma_f32_16x16x32_bf16 v[50:53], v[138:141], v[238:241], v[50:53]
	v_mfma_f32_16x16x32_bf16 v[54:57], v[138:141], v[242:245], v[54:57]
	v_mfma_f32_16x16x32_bf16 v[58:61], v[142:145], v[238:241], v[58:61]
	v_mfma_f32_16x16x32_bf16 v[62:65], v[142:145], v[242:245], v[62:65]
	v_add_u32_e32 v237, s99, v181
	ds_read_b128 v[130:133], v237 offset:24576
	ds_read_b128 v[134:137], v237 offset:26624
	ds_read_b128 v[138:141], v237 offset:28672
	ds_read_b128 v[142:145], v237 offset:30720
	s_waitcnt lgkmcnt(4)
	v_mfma_f32_16x16x32_bf16 v[2:5], v[146:149], v[246:249], v[2:5]
	v_mfma_f32_16x16x32_bf16 v[6:9], v[146:149], v[250:253], v[6:9]
	v_mfma_f32_16x16x32_bf16 v[10:13], v[150:153], v[246:249], v[10:13]
	v_mfma_f32_16x16x32_bf16 v[14:17], v[150:153], v[250:253], v[14:17]
	v_mfma_f32_16x16x32_bf16 v[18:21], v[154:157], v[246:249], v[18:21]
	v_mfma_f32_16x16x32_bf16 v[22:25], v[154:157], v[250:253], v[22:25]
	v_mfma_f32_16x16x32_bf16 v[26:29], v[158:161], v[246:249], v[26:29]
	v_mfma_f32_16x16x32_bf16 v[30:33], v[158:161], v[250:253], v[30:33]
	s_waitcnt lgkmcnt(0)
	v_mfma_f32_16x16x32_bf16 v[34:37], v[130:133], v[246:249], v[34:37]
	v_mfma_f32_16x16x32_bf16 v[38:41], v[130:133], v[250:253], v[38:41]
	v_mfma_f32_16x16x32_bf16 v[42:45], v[134:137], v[246:249], v[42:45]
	v_mfma_f32_16x16x32_bf16 v[46:49], v[134:137], v[250:253], v[46:49]
	v_mfma_f32_16x16x32_bf16 v[50:53], v[138:141], v[246:249], v[50:53]
	v_mfma_f32_16x16x32_bf16 v[54:57], v[138:141], v[250:253], v[54:57]
	v_mfma_f32_16x16x32_bf16 v[58:61], v[142:145], v[246:249], v[58:61]
	v_mfma_f32_16x16x32_bf16 v[62:65], v[142:145], v[250:253], v[62:65]
	s_branch .LBB0_286

; template <bool WIN> ...
;     ...
;     asm volatile("s_waitcnt lgkmcnt(0)\n\ts_barrier" ::: "memory");
;     ...
;     const float l_tot = l_run + __shfl_xor(l_run, 32);
;     const float inv = 1.0f / l_tot;
;     const size_t orow = (size_t)(seq_base + qw + l31) * 1024;
.LBB0_286:
	ds_bpermute_b32 v66, v176, v0
	s_waitcnt lgkmcnt(0)
	s_barrier
	s_nop 7
	v_mbcnt_lo_u32_b32 v82, -1, 0
	v_mbcnt_hi_u32_b32 v82, -1, v82
	v_and_b32_e32 v83, 15, v82
	v_lshrrev_b32_e32 v84, 4, v82
	v_and_b32_e32 v85, 2, v84
	v_lshrrev_b32_e32 v86, 1, v84
	v_xor_b32_e32 v86, v86, v84
	v_and_b32_e32 v86, 1, v86
	v_xor_b32_e32 v86, 1, v86
	v_lshlrev_b32_e32 v86, 3, v86
	s_add_i32 s98, s29, 0x1000
	s_and_b32 s98, s98, 0x1c00
	s_lshl_b32 s98, s98, 4
	v_lshl_add_u32 v87, v83, 9, v86
	v_add_u32_e32 v87, s98, v87
	v_add_u32_e32 v88, 0x2000, v87
	v_xor_b32_e32 v89, v85, v83
	v_lshlrev_b32_e32 v89, 4, v89
	v_xor_b32_e32 v90, 0x100, v89
	v_xor_b32_e32 v91, 0x0, v89
	v_add_u32_e32 v91, v87, v91
	ds_write_b64 v91, v[2:3]
	v_xor_b32_e32 v91, 0x10, v89
	v_add_u32_e32 v91, v87, v91
	ds_write_b64 v91, v[4:5]
	v_xor_b32_e32 v91, 0x0, v90
	v_add_u32_e32 v91, v88, v91
	ds_write_b64 v91, v[6:7]
	v_xor_b32_e32 v91, 0x10, v90
	v_add_u32_e32 v91, v88, v91
	ds_write_b64 v91, v[8:9]
	v_xor_b32_e32 v91, 0x40, v89
	v_add_u32_e32 v91, v87, v91
	ds_write_b64 v91, v[10:11]
	v_xor_b32_e32 v91, 0x50, v89
	v_add_u32_e32 v91, v87, v91
	ds_write_b64 v91, v[12:13]
	v_xor_b32_e32 v91, 0x40, v90
	v_add_u32_e32 v91, v88, v91
	ds_write_b64 v91, v[14:15]
	v_xor_b32_e32 v91, 0x50, v90
	v_add_u32_e32 v91, v88, v91
	ds_write_b64 v91, v[16:17]
	s_waitcnt lgkmcnt(0)
	v_xor_b32_e32 v91, 0x80, v89
	v_add_u32_e32 v91, v87, v91
	ds_write_b64 v91, v[18:19]
	v_xor_b32_e32 v91, 0x90, v89
	v_add_u32_e32 v91, v87, v91
	ds_write_b64 v91, v[20:21]
	v_xor_b32_e32 v91, 0x80, v90
	v_add_u32_e32 v91, v88, v91
	ds_write_b64 v91, v[22:23]
	v_xor_b32_e32 v91, 0x90, v90
	v_add_u32_e32 v91, v88, v91
	ds_write_b64 v91, v[24:25]
	v_xor_b32_e32 v91, 0xc0, v89
	v_add_u32_e32 v91, v87, v91
	ds_write_b64 v91, v[26:27]
	v_xor_b32_e32 v91, 0xd0, v89
	v_add_u32_e32 v91, v87, v91
	ds_write_b64 v91, v[28:29]
	v_xor_b32_e32 v91, 0xc0, v90
	v_add_u32_e32 v91, v88, v91
	ds_write_b64 v91, v[30:31]
	v_xor_b32_e32 v91, 0xd0, v90
	v_add_u32_e32 v91, v88, v91
	ds_write_b64 v91, v[32:33]
	s_waitcnt lgkmcnt(0)
	v_xor_b32_e32 v91, 0x100, v89
	v_add_u32_e32 v91, v87, v91
	ds_write_b64 v91, v[34:35]
	v_xor_b32_e32 v91, 0x110, v89
	v_add_u32_e32 v91, v87, v91
	ds_write_b64 v91, v[36:37]
	v_xor_b32_e32 v91, 0x100, v90
	v_add_u32_e32 v91, v88, v91
	ds_write_b64 v91, v[38:39]
	v_xor_b32_e32 v91, 0x110, v90
	v_add_u32_e32 v91, v88, v91
	ds_write_b64 v91, v[40:41]
	v_xor_b32_e32 v91, 0x140, v89
	v_add_u32_e32 v91, v87, v91
	ds_write_b64 v91, v[42:43]
	v_xor_b32_e32 v91, 0x150, v89
	v_add_u32_e32 v91, v87, v91
	ds_write_b64 v91, v[44:45]
	v_xor_b32_e32 v91, 0x140, v90
	v_add_u32_e32 v91, v88, v91
	ds_write_b64 v91, v[46:47]
	v_xor_b32_e32 v91, 0x150, v90
	v_add_u32_e32 v91, v88, v91
	ds_write_b64 v91, v[48:49]
	s_waitcnt lgkmcnt(0)
	v_xor_b32_e32 v91, 0x180, v89
	v_add_u32_e32 v91, v87, v91
	ds_write_b64 v91, v[50:51]
	v_xor_b32_e32 v91, 0x190, v89
	v_add_u32_e32 v91, v87, v91
	ds_write_b64 v91, v[52:53]
	v_xor_b32_e32 v91, 0x180, v90
	v_add_u32_e32 v91, v88, v91
	ds_write_b64 v91, v[54:55]
	v_xor_b32_e32 v91, 0x190, v90
	v_add_u32_e32 v91, v88, v91
	ds_write_b64 v91, v[56:57]
	v_xor_b32_e32 v91, 0x1c0, v89
	v_add_u32_e32 v91, v87, v91
	ds_write_b64 v91, v[58:59]
	v_xor_b32_e32 v91, 0x1d0, v89
	v_add_u32_e32 v91, v87, v91
	ds_write_b64 v91, v[60:61]
	v_xor_b32_e32 v91, 0x1c0, v90
	v_add_u32_e32 v91, v88, v91
	ds_write_b64 v91, v[62:63]
	v_xor_b32_e32 v91, 0x1d0, v90
	v_add_u32_e32 v91, v88, v91
	ds_write_b64 v91, v[64:65]
	s_waitcnt lgkmcnt(0)
	v_and_b32_e32 v83, 31, v82
	v_lshrrev_b32_e32 v84, 5, v82
	v_lshlrev_b32_e32 v87, 9, v83
	v_add_u32_e32 v87, s98, v87
	v_xor_b32_e32 v89, v84, v83
	v_lshlrev_b32_e32 v89, 4, v89
	v_xor_b32_e32 v91, 0x0, v89
	v_add_u32_e32 v91, v87, v91
	ds_read_b128 v[50:53], v91
	v_xor_b32_e32 v91, 0x20, v89
	v_add_u32_e32 v91, v87, v91
	ds_read_b128 v[54:57], v91
	v_xor_b32_e32 v91, 0x40, v89
	v_add_u32_e32 v91, v87, v91
	ds_read_b128 v[58:61], v91
	v_xor_b32_e32 v91, 0x60, v89
	v_add_u32_e32 v91, v87, v91
	ds_read_b128 v[62:65], v91
	v_xor_b32_e32 v91, 0x80, v89
	v_add_u32_e32 v91, v87, v91
	ds_read_b128 v[34:37], v91
	v_xor_b32_e32 v91, 0xa0, v89
	v_add_u32_e32 v91, v87, v91
	ds_read_b128 v[38:41], v91
	v_xor_b32_e32 v91, 0xc0, v89
	v_add_u32_e32 v91, v87, v91
	ds_read_b128 v[42:45], v91
	v_xor_b32_e32 v91, 0xe0, v89
	v_add_u32_e32 v91, v87, v91
	ds_read_b128 v[46:49], v91
	s_waitcnt lgkmcnt(0)
	v_xor_b32_e32 v91, 0x100, v89
	v_add_u32_e32 v91, v87, v91
	ds_read_b128 v[18:21], v91
	v_xor_b32_e32 v91, 0x120, v89
	v_add_u32_e32 v91, v87, v91
	ds_read_b128 v[22:25], v91
	v_xor_b32_e32 v91, 0x140, v89
	v_add_u32_e32 v91, v87, v91
	ds_read_b128 v[26:29], v91
	v_xor_b32_e32 v91, 0x160, v89
	v_add_u32_e32 v91, v87, v91
	ds_read_b128 v[30:33], v91
	v_xor_b32_e32 v91, 0x180, v89
	v_add_u32_e32 v91, v87, v91
	ds_read_b128 v[2:5], v91
	v_xor_b32_e32 v91, 0x1a0, v89
	v_add_u32_e32 v91, v87, v91
	ds_read_b128 v[6:9], v91
	v_xor_b32_e32 v91, 0x1c0, v89
	v_add_u32_e32 v91, v87, v91
	ds_read_b128 v[10:13], v91
	v_xor_b32_e32 v91, 0x1e0, v89
	v_add_u32_e32 v91, v87, v91
	ds_read_b128 v[14:17], v91
	s_waitcnt lgkmcnt(0)
	v_bfe_u32 v83, v82, 1, 3
	v_xor_b32_e32 v85, v84, v83
	v_lshlrev_b32_e32 v179, 4, v85
	v_or_b32_e32 v84, 2, v84
	v_xor_b32_e32 v85, v84, v83
	v_lshlrev_b32_e32 v181, 4, v85
	v_lshl_add_u32 v67, s27, 14, v192
	s_cmp_lg_u32 s26, 1
	s_waitcnt lgkmcnt(0)
	v_add_f32_e32 v0, v0, v66
	v_div_scale_f32 v66, s[28:29], v0, v0, 1.0
	v_rcp_f32_e32 v68, v66
	v_div_scale_f32 v69, vcc, 1.0, v0, 1.0
	v_fma_f32 v70, -v66, v68, 1.0
	v_fmac_f32_e32 v68, v70, v68
	v_mul_f32_e32 v70, v69, v68
	v_fma_f32 v71, -v66, v70, v69
	v_fmac_f32_e32 v70, v71, v68
	v_fma_f32 v66, -v66, v70, v69
	v_div_fmas_f32 v66, v66, v68, v70
	v_div_fixup_f32 v162, v66, v0, 1.0
	v_add_u32_e32 v0, v67, v193
	s_cbranch_scc1 .LBB0_288
; #define ALAS __attribute__((address_space(3)))
; template <bool WIN> ...
;     ...
;         ALAS f32x4* xch = (ALAS f32x4*)lds + (size_t)wq * 1024 + l31;
;         if (half == 1) {
; #pragma unroll
;             for (int db = 0; db < NDB; ++db)
; #pragma unroll
;                 for (int g = 0; g < 4; ++g) { f32x4 v; v[0] = o[db][4 * g] * inv; v[1] = o[db][4 * g + 1] * inv; v[2] = o[db][4 * g + 2] * inv; v[3] = o[db][4 * g + 3] * inv;
;                     xch[(8 * db + 2 * g + hi) * 32] = v; }
	v_pk_mul_f32 v[66:67], v[50:51], v[162:163] op_sel_hi:[1,0]
	v_pk_mul_f32 v[68:69], v[52:53], v[162:163] op_sel_hi:[1,0]
	ds_write_b128 v0, v[66:69]
	v_pk_mul_f32 v[66:67], v[54:55], v[162:163] op_sel_hi:[1,0]
	v_pk_mul_f32 v[68:69], v[56:57], v[162:163] op_sel_hi:[1,0]
	ds_write_b128 v0, v[66:69] offset:1024
	v_pk_mul_f32 v[66:67], v[58:59], v[162:163] op_sel_hi:[1,0]
	v_pk_mul_f32 v[68:69], v[60:61], v[162:163] op_sel_hi:[1,0]
	ds_write_b128 v0, v[66:69] offset:2048
	v_pk_mul_f32 v[66:67], v[62:63], v[162:163] op_sel_hi:[1,0]
	v_pk_mul_f32 v[68:69], v[64:65], v[162:163] op_sel_hi:[1,0]
	ds_write_b128 v0, v[66:69] offset:3072
	v_pk_mul_f32 v[66:67], v[34:35], v[162:163] op_sel_hi:[1,0]
	v_pk_mul_f32 v[68:69], v[36:37], v[162:163] op_sel_hi:[1,0]
	ds_write_b128 v0, v[66:69] offset:4096
	v_pk_mul_f32 v[66:67], v[38:39], v[162:163] op_sel_hi:[1,0]
	v_pk_mul_f32 v[68:69], v[40:41], v[162:163] op_sel_hi:[1,0]
	ds_write_b128 v0, v[66:69] offset:5120
	v_pk_mul_f32 v[66:67], v[42:43], v[162:163] op_sel_hi:[1,0]
	v_pk_mul_f32 v[68:69], v[44:45], v[162:163] op_sel_hi:[1,0]
	ds_write_b128 v0, v[66:69] offset:6144
	v_pk_mul_f32 v[66:67], v[46:47], v[162:163] op_sel_hi:[1,0]
	v_pk_mul_f32 v[68:69], v[48:49], v[162:163] op_sel_hi:[1,0]
	ds_write_b128 v0, v[66:69] offset:7168
	v_pk_mul_f32 v[66:67], v[18:19], v[162:163] op_sel_hi:[1,0]
	v_pk_mul_f32 v[68:69], v[20:21], v[162:163] op_sel_hi:[1,0]
	ds_write_b128 v0, v[66:69] offset:8192
	v_pk_mul_f32 v[66:67], v[22:23], v[162:163] op_sel_hi:[1,0]
	v_pk_mul_f32 v[68:69], v[24:25], v[162:163] op_sel_hi:[1,0]
	ds_write_b128 v0, v[66:69] offset:9216
	v_pk_mul_f32 v[66:67], v[26:27], v[162:163] op_sel_hi:[1,0]
	v_pk_mul_f32 v[68:69], v[28:29], v[162:163] op_sel_hi:[1,0]
	ds_write_b128 v0, v[66:69] offset:10240
	v_pk_mul_f32 v[66:67], v[30:31], v[162:163] op_sel_hi:[1,0]
	v_pk_mul_f32 v[68:69], v[32:33], v[162:163] op_sel_hi:[1,0]
	ds_write_b128 v0, v[66:69] offset:11264
	v_pk_mul_f32 v[66:67], v[2:3], v[162:163] op_sel_hi:[1,0]
	v_pk_mul_f32 v[68:69], v[4:5], v[162:163] op_sel_hi:[1,0]
	ds_write_b128 v0, v[66:69] offset:12288
	v_pk_mul_f32 v[66:67], v[6:7], v[162:163] op_sel_hi:[1,0]
	v_pk_mul_f32 v[68:69], v[8:9], v[162:163] op_sel_hi:[1,0]
	ds_write_b128 v0, v[66:69] offset:13312
	v_pk_mul_f32 v[66:67], v[10:11], v[162:163] op_sel_hi:[1,0]
	v_pk_mul_f32 v[68:69], v[12:13], v[162:163] op_sel_hi:[1,0]
	ds_write_b128 v0, v[66:69] offset:14336
	v_pk_mul_f32 v[66:67], v[14:15], v[162:163] op_sel_hi:[1,0]
	v_pk_mul_f32 v[68:69], v[16:17], v[162:163] op_sel_hi:[1,0]
	ds_write_b128 v0, v[66:69] offset:15360
